# per-phase counted vmcnt(10) in 8-phase K loops: retire each half-tile one phase before first read (5 stages in flight instead of 3)
# baseline (speedup 1.0000x reference)
.LBB0_242:
	s_add_u32 s4, s0, 0xfffc0080
	s_addc_u32 s5, s1, -1
	s_add_i32 vcc_lo, 0, 0x10000
	v_add_u32_e32 v128, vcc_lo, v162
	ds_read_b128 v[142:145], v128
	ds_read_b128 v[146:149], v128 offset:1024
	ds_read_b128 v[150:153], v128 offset:2048
	ds_read_b128 v[154:157], v128 offset:3072
	s_cmp_eq_u32 s75, 12
	s_cselect_b32 s37, s22, s5
	s_cselect_b32 s36, s23, s4
	s_cselect_b32 s5, s7, s39
	s_cselect_b32 s4, s25, s38
	v_lshl_add_u64 v[196:197], s[0:1], 0, v[138:139]
	s_add_i32 m0, s95, 0xc000
	ds_read_b128 v[164:167], v163
	ds_read_b128 v[168:171], v163 offset:1024
	ds_read_b128 v[172:175], v163 offset:2048
	ds_read_b128 v[176:179], v163 offset:3072
	ds_read_b128 v[180:183], v163 offset:4096
	ds_read_b128 v[184:187], v163 offset:5120
	ds_read_b128 v[188:191], v163 offset:6144
	ds_read_b128 v[192:195], v163 offset:7168
	global_load_lds_dwordx4 v[196:197], off
	v_lshl_add_u64 v[196:197], s[0:1], 0, v[140:141]
	s_add_i32 m0, s95, 0xe000
	s_nop 0
	global_load_lds_dwordx4 v[196:197], off
	s_waitcnt lgkmcnt(8)
	s_waitcnt vmcnt(10)
	s_barrier
	s_waitcnt lgkmcnt(0)
	s_setprio 1
	s_waitcnt lgkmcnt(0)
	v_mfma_f32_16x16x32_bf16 v[124:127], v[142:145], v[164:167], v[124:127]
	v_mfma_f32_16x16x32_bf16 v[120:123], v[150:153], v[164:167], v[120:123]
	v_mfma_f32_16x16x32_bf16 v[108:111], v[142:145], v[172:175], v[108:111]
	v_mfma_f32_16x16x32_bf16 v[104:107], v[150:153], v[172:175], v[104:107]
	v_mfma_f32_16x16x32_bf16 v[92:95], v[142:145], v[180:183], v[92:95]
	v_mfma_f32_16x16x32_bf16 v[88:91], v[150:153], v[180:183], v[88:91]
	v_mfma_f32_16x16x32_bf16 v[76:79], v[142:145], v[188:191], v[76:79]
	v_mfma_f32_16x16x32_bf16 v[72:75], v[150:153], v[188:191], v[72:75]
	v_mfma_f32_16x16x32_bf16 v[124:127], v[146:149], v[168:171], v[124:127]
	v_mfma_f32_16x16x32_bf16 v[120:123], v[154:157], v[168:171], v[120:123]
	v_mfma_f32_16x16x32_bf16 v[108:111], v[146:149], v[176:179], v[108:111]
	v_mfma_f32_16x16x32_bf16 v[104:107], v[154:157], v[176:179], v[104:107]
	v_mfma_f32_16x16x32_bf16 v[92:95], v[146:149], v[184:187], v[92:95]
	v_mfma_f32_16x16x32_bf16 v[88:91], v[154:157], v[184:187], v[88:91]
	v_mfma_f32_16x16x32_bf16 v[76:79], v[146:149], v[192:195], v[76:79]
	v_mfma_f32_16x16x32_bf16 v[72:75], v[154:157], v[192:195], v[72:75]
	s_setprio 0
	s_barrier
	s_add_i32 s26, 0, 0x14000
	s_add_i32 s27, vcc_lo, s87
	v_add_u32_e32 v128, s26, v162
	v_lshl_add_u64 v[200:201], s[4:5], 0, v[132:133]
	s_mov_b32 m0, s27
	ds_read_b128 v[196:199], v128
	ds_read_b128 v[210:213], v128 offset:1024
	ds_read_b128 v[214:217], v128 offset:2048
	ds_read_b128 v[218:221], v128 offset:3072
	global_load_lds_dwordx4 v[200:201], off
	v_lshl_add_u64 v[222:223], s[4:5], 0, v[136:137]
	s_add_i32 m0, s27, 0x2000
	s_nop 0
	global_load_lds_dwordx4 v[222:223], off
	s_waitcnt vmcnt(10)
	s_barrier
	s_waitcnt lgkmcnt(0)
	s_setprio 1
	s_waitcnt lgkmcnt(0)
	v_mfma_f32_16x16x32_bf16 v[116:119], v[196:199], v[164:167], v[116:119]
	v_mfma_f32_16x16x32_bf16 v[112:115], v[214:217], v[164:167], v[112:115]
	v_mfma_f32_16x16x32_bf16 v[100:103], v[196:199], v[172:175], v[100:103]
	v_mfma_f32_16x16x32_bf16 v[96:99], v[214:217], v[172:175], v[96:99]
	v_mfma_f32_16x16x32_bf16 v[84:87], v[196:199], v[180:183], v[84:87]
	v_mfma_f32_16x16x32_bf16 v[80:83], v[214:217], v[180:183], v[80:83]
	v_mfma_f32_16x16x32_bf16 v[68:71], v[196:199], v[188:191], v[68:71]
	v_mfma_f32_16x16x32_bf16 v[64:67], v[214:217], v[188:191], v[64:67]
	v_mfma_f32_16x16x32_bf16 v[116:119], v[210:213], v[168:171], v[116:119]
	v_mfma_f32_16x16x32_bf16 v[112:115], v[218:221], v[168:171], v[112:115]
	v_mfma_f32_16x16x32_bf16 v[100:103], v[210:213], v[176:179], v[100:103]
	v_mfma_f32_16x16x32_bf16 v[96:99], v[218:221], v[176:179], v[96:99]
	v_mfma_f32_16x16x32_bf16 v[84:87], v[210:213], v[184:187], v[84:87]
	v_mfma_f32_16x16x32_bf16 v[80:83], v[218:221], v[184:187], v[80:83]
	v_mfma_f32_16x16x32_bf16 v[68:71], v[210:213], v[192:195], v[68:71]
	v_mfma_f32_16x16x32_bf16 v[64:67], v[218:221], v[192:195], v[64:67]
	s_setprio 0
	s_mov_b32 m0, s95
	v_lshl_add_u64 v[224:225], s[36:37], 0, v[130:131]
	s_barrier
	ds_read_b128 v[164:167], v163 offset:16384
	ds_read_b128 v[168:171], v163 offset:17408
	ds_read_b128 v[172:175], v163 offset:18432
	ds_read_b128 v[176:179], v163 offset:19456
	ds_read_b128 v[180:183], v163 offset:20480
	ds_read_b128 v[184:187], v163 offset:21504
	ds_read_b128 v[188:191], v163 offset:22528
	ds_read_b128 v[192:195], v163 offset:23552
	global_load_lds_dwordx4 v[224:225], off
	v_lshl_add_u64 v[226:227], s[36:37], 0, v[134:135]
	s_mov_b32 m0, s97
	s_nop 0
	global_load_lds_dwordx4 v[226:227], off
	s_barrier
	s_waitcnt lgkmcnt(0)
	s_setprio 1
	s_waitcnt lgkmcnt(0)
	v_mfma_f32_16x16x32_bf16 v[60:63], v[142:145], v[164:167], v[60:63]
	v_mfma_f32_16x16x32_bf16 v[56:59], v[150:153], v[164:167], v[56:59]
	v_mfma_f32_16x16x32_bf16 v[44:47], v[142:145], v[172:175], v[44:47]
	v_mfma_f32_16x16x32_bf16 v[40:43], v[150:153], v[172:175], v[40:43]
	v_mfma_f32_16x16x32_bf16 v[28:31], v[142:145], v[180:183], v[28:31]
	v_mfma_f32_16x16x32_bf16 v[24:27], v[150:153], v[180:183], v[24:27]
	v_mfma_f32_16x16x32_bf16 v[12:15], v[142:145], v[188:191], v[12:15]
	v_mfma_f32_16x16x32_bf16 v[8:11], v[150:153], v[188:191], v[8:11]
	v_mfma_f32_16x16x32_bf16 v[60:63], v[146:149], v[168:171], v[60:63]
	v_mfma_f32_16x16x32_bf16 v[56:59], v[154:157], v[168:171], v[56:59]
	v_mfma_f32_16x16x32_bf16 v[44:47], v[146:149], v[176:179], v[44:47]
	v_mfma_f32_16x16x32_bf16 v[40:43], v[154:157], v[176:179], v[40:43]
	v_mfma_f32_16x16x32_bf16 v[28:31], v[146:149], v[184:187], v[28:31]
	v_mfma_f32_16x16x32_bf16 v[24:27], v[154:157], v[184:187], v[24:27]
	v_mfma_f32_16x16x32_bf16 v[12:15], v[146:149], v[192:195], v[12:15]
	v_mfma_f32_16x16x32_bf16 v[8:11], v[154:157], v[192:195], v[8:11]
	s_setprio 0
	s_barrier
	s_add_u32 vcc_lo, s4, 0x40000
	s_addc_u32 vcc_hi, s5, 0
	s_add_i32 s26, s26, s87
	v_lshl_add_u64 v[142:143], vcc, 0, v[132:133]
	s_mov_b32 m0, s26
	s_nop 0
	global_load_lds_dwordx4 v[142:143], off
	v_lshl_add_u64 v[142:143], vcc, 0, v[136:137]
	s_add_i32 m0, s26, 0x2000
	s_nop 0
	global_load_lds_dwordx4 v[142:143], off
	s_waitcnt vmcnt(10)
	s_barrier
	s_setprio 1
	v_mfma_f32_16x16x32_bf16 v[52:55], v[196:199], v[164:167], v[52:55]
	v_mfma_f32_16x16x32_bf16 v[48:51], v[214:217], v[164:167], v[48:51]
	v_mfma_f32_16x16x32_bf16 v[36:39], v[196:199], v[172:175], v[36:39]
	v_mfma_f32_16x16x32_bf16 v[32:35], v[214:217], v[172:175], v[32:35]
	v_mfma_f32_16x16x32_bf16 v[20:23], v[196:199], v[180:183], v[20:23]
	v_mfma_f32_16x16x32_bf16 v[16:19], v[214:217], v[180:183], v[16:19]
	v_mfma_f32_16x16x32_bf16 v[4:7], v[196:199], v[188:191], v[4:7]
	v_mfma_f32_16x16x32_bf16 v[0:3], v[214:217], v[188:191], v[0:3]
	v_mfma_f32_16x16x32_bf16 v[52:55], v[210:213], v[168:171], v[52:55]
	v_mfma_f32_16x16x32_bf16 v[48:51], v[218:221], v[168:171], v[48:51]
	v_mfma_f32_16x16x32_bf16 v[36:39], v[210:213], v[176:179], v[36:39]
	v_mfma_f32_16x16x32_bf16 v[32:35], v[218:221], v[176:179], v[32:35]
	v_mfma_f32_16x16x32_bf16 v[20:23], v[210:213], v[184:187], v[20:23]
	v_mfma_f32_16x16x32_bf16 v[16:19], v[218:221], v[184:187], v[16:19]
	v_mfma_f32_16x16x32_bf16 v[4:7], v[210:213], v[192:195], v[4:7]
	v_mfma_f32_16x16x32_bf16 v[0:3], v[218:221], v[192:195], v[0:3]
	s_setprio 0
	s_add_i32 s26, 0, 0x18000
	v_add_u32_e32 v128, s26, v162
	s_barrier
	ds_read_b128 v[142:145], v128
	ds_read_b128 v[146:149], v128 offset:1024
	ds_read_b128 v[150:153], v128 offset:2048
	ds_read_b128 v[154:157], v128 offset:3072
	s_add_u32 s36, s36, 0x40000
	s_addc_u32 s37, s37, 0
	s_mov_b32 m0, s33
	v_lshl_add_u64 v[196:197], s[36:37], 0, v[130:131]
	ds_read_b128 v[164:167], v163 offset:32768
	ds_read_b128 v[168:171], v163 offset:33792
	ds_read_b128 v[172:175], v163 offset:34816
	ds_read_b128 v[176:179], v163 offset:35840
	ds_read_b128 v[180:183], v163 offset:36864
	ds_read_b128 v[184:187], v163 offset:37888
	ds_read_b128 v[188:191], v163 offset:38912
	ds_read_b128 v[192:195], v163 offset:39936
	global_load_lds_dwordx4 v[196:197], off
	v_lshl_add_u64 v[196:197], s[36:37], 0, v[134:135]
	s_mov_b32 m0, s93
	s_nop 0
	global_load_lds_dwordx4 v[196:197], off
	s_waitcnt lgkmcnt(8)
	s_waitcnt vmcnt(10)
	s_barrier
	s_waitcnt lgkmcnt(0)
	s_setprio 1
	s_waitcnt lgkmcnt(0)
	v_mfma_f32_16x16x32_bf16 v[124:127], v[142:145], v[164:167], v[124:127]
	v_mfma_f32_16x16x32_bf16 v[120:123], v[150:153], v[164:167], v[120:123]
	v_mfma_f32_16x16x32_bf16 v[108:111], v[142:145], v[172:175], v[108:111]
	v_mfma_f32_16x16x32_bf16 v[104:107], v[150:153], v[172:175], v[104:107]
	v_mfma_f32_16x16x32_bf16 v[92:95], v[142:145], v[180:183], v[92:95]
	v_mfma_f32_16x16x32_bf16 v[88:91], v[150:153], v[180:183], v[88:91]
	v_mfma_f32_16x16x32_bf16 v[76:79], v[142:145], v[188:191], v[76:79]
	v_mfma_f32_16x16x32_bf16 v[72:75], v[150:153], v[188:191], v[72:75]
	v_mfma_f32_16x16x32_bf16 v[124:127], v[146:149], v[168:171], v[124:127]
	v_mfma_f32_16x16x32_bf16 v[120:123], v[154:157], v[168:171], v[120:123]
	v_mfma_f32_16x16x32_bf16 v[108:111], v[146:149], v[176:179], v[108:111]
	v_mfma_f32_16x16x32_bf16 v[104:107], v[154:157], v[176:179], v[104:107]
	v_mfma_f32_16x16x32_bf16 v[92:95], v[146:149], v[184:187], v[92:95]
	v_mfma_f32_16x16x32_bf16 v[88:91], v[154:157], v[184:187], v[88:91]
	v_mfma_f32_16x16x32_bf16 v[76:79], v[146:149], v[192:195], v[76:79]
	v_mfma_f32_16x16x32_bf16 v[72:75], v[154:157], v[192:195], v[72:75]
	s_setprio 0
	s_barrier
	s_add_i32 s27, 0, 0x1c000
	s_add_i32 s26, s26, s87
	v_add_u32_e32 v128, s27, v162
	v_lshl_add_u64 v[200:201], v[200:201], 0, s[82:83]
	s_mov_b32 m0, s26
	ds_read_b128 v[196:199], v128
	ds_read_b128 v[210:213], v128 offset:1024
	ds_read_b128 v[214:217], v128 offset:2048
	ds_read_b128 v[218:221], v128 offset:3072
	global_load_lds_dwordx4 v[200:201], off
	v_lshl_add_u64 v[200:201], v[222:223], 0, s[82:83]
	s_add_i32 m0, s26, 0x2000
	s_nop 0
	global_load_lds_dwordx4 v[200:201], off
	s_waitcnt vmcnt(10)
	s_barrier
	s_waitcnt lgkmcnt(0)
	s_setprio 1
	s_waitcnt lgkmcnt(0)
	v_mfma_f32_16x16x32_bf16 v[116:119], v[196:199], v[164:167], v[116:119]
	v_mfma_f32_16x16x32_bf16 v[112:115], v[214:217], v[164:167], v[112:115]
	v_mfma_f32_16x16x32_bf16 v[100:103], v[196:199], v[172:175], v[100:103]
	v_mfma_f32_16x16x32_bf16 v[96:99], v[214:217], v[172:175], v[96:99]
	v_mfma_f32_16x16x32_bf16 v[84:87], v[196:199], v[180:183], v[84:87]
	v_mfma_f32_16x16x32_bf16 v[80:83], v[214:217], v[180:183], v[80:83]
	v_mfma_f32_16x16x32_bf16 v[68:71], v[196:199], v[188:191], v[68:71]
	v_mfma_f32_16x16x32_bf16 v[64:67], v[214:217], v[188:191], v[64:67]
	v_mfma_f32_16x16x32_bf16 v[116:119], v[210:213], v[168:171], v[116:119]
	v_mfma_f32_16x16x32_bf16 v[112:115], v[218:221], v[168:171], v[112:115]
	v_mfma_f32_16x16x32_bf16 v[100:103], v[210:213], v[176:179], v[100:103]
	v_mfma_f32_16x16x32_bf16 v[96:99], v[218:221], v[176:179], v[96:99]
	v_mfma_f32_16x16x32_bf16 v[84:87], v[210:213], v[184:187], v[84:87]
	v_mfma_f32_16x16x32_bf16 v[80:83], v[218:221], v[184:187], v[80:83]
	v_mfma_f32_16x16x32_bf16 v[68:71], v[210:213], v[192:195], v[68:71]
	v_mfma_f32_16x16x32_bf16 v[64:67], v[218:221], v[192:195], v[64:67]
	s_setprio 0
	s_mov_b32 m0, s12
	v_lshl_add_u64 v[200:201], v[224:225], 0, s[82:83]
	s_barrier
	ds_read_b128 v[164:167], v163 offset:49152
	ds_read_b128 v[168:171], v163 offset:50176
	ds_read_b128 v[172:175], v163 offset:51200
	ds_read_b128 v[176:179], v163 offset:52224
	ds_read_b128 v[180:183], v163 offset:53248
	ds_read_b128 v[184:187], v163 offset:54272
	ds_read_b128 v[188:191], v163 offset:55296
	ds_read_b128 v[192:195], v163 offset:56320
	global_load_lds_dwordx4 v[200:201], off
	v_lshl_add_u64 v[200:201], v[226:227], 0, s[82:83]
	s_mov_b32 m0, s13
	s_nop 0
	global_load_lds_dwordx4 v[200:201], off
	s_barrier
	s_waitcnt lgkmcnt(0)
	s_setprio 1
	s_waitcnt lgkmcnt(0)
	v_mfma_f32_16x16x32_bf16 v[60:63], v[142:145], v[164:167], v[60:63]
	v_mfma_f32_16x16x32_bf16 v[56:59], v[150:153], v[164:167], v[56:59]
	v_mfma_f32_16x16x32_bf16 v[44:47], v[142:145], v[172:175], v[44:47]
	v_mfma_f32_16x16x32_bf16 v[40:43], v[150:153], v[172:175], v[40:43]
	v_mfma_f32_16x16x32_bf16 v[28:31], v[142:145], v[180:183], v[28:31]
	v_mfma_f32_16x16x32_bf16 v[24:27], v[150:153], v[180:183], v[24:27]
	v_mfma_f32_16x16x32_bf16 v[12:15], v[142:145], v[188:191], v[12:15]
	v_mfma_f32_16x16x32_bf16 v[8:11], v[150:153], v[188:191], v[8:11]
	v_mfma_f32_16x16x32_bf16 v[60:63], v[146:149], v[168:171], v[60:63]
	v_mfma_f32_16x16x32_bf16 v[56:59], v[154:157], v[168:171], v[56:59]
	v_mfma_f32_16x16x32_bf16 v[44:47], v[146:149], v[176:179], v[44:47]
	v_mfma_f32_16x16x32_bf16 v[40:43], v[154:157], v[176:179], v[40:43]
	v_mfma_f32_16x16x32_bf16 v[28:31], v[146:149], v[184:187], v[28:31]
	v_mfma_f32_16x16x32_bf16 v[24:27], v[154:157], v[184:187], v[24:27]
	v_mfma_f32_16x16x32_bf16 v[12:15], v[146:149], v[192:195], v[12:15]
	v_mfma_f32_16x16x32_bf16 v[8:11], v[154:157], v[192:195], v[8:11]
	s_setprio 0
	s_barrier
	s_add_u32 s4, s4, 0x40080
	s_addc_u32 s5, s5, 0
	s_add_i32 s26, s27, s87
	v_lshl_add_u64 v[142:143], s[4:5], 0, v[132:133]
	s_mov_b32 m0, s26
	s_nop 0
	global_load_lds_dwordx4 v[142:143], off
	v_lshl_add_u64 v[142:143], s[4:5], 0, v[136:137]
	s_add_i32 m0, s26, 0x2000
	s_nop 0
	global_load_lds_dwordx4 v[142:143], off
	s_waitcnt vmcnt(10)
	s_barrier
	s_setprio 1
	v_mfma_f32_16x16x32_bf16 v[52:55], v[196:199], v[164:167], v[52:55]
	v_mfma_f32_16x16x32_bf16 v[48:51], v[214:217], v[164:167], v[48:51]
	v_mfma_f32_16x16x32_bf16 v[36:39], v[196:199], v[172:175], v[36:39]
	v_mfma_f32_16x16x32_bf16 v[32:35], v[214:217], v[172:175], v[32:35]
	v_mfma_f32_16x16x32_bf16 v[20:23], v[196:199], v[180:183], v[20:23]
	v_mfma_f32_16x16x32_bf16 v[16:19], v[214:217], v[180:183], v[16:19]
	v_mfma_f32_16x16x32_bf16 v[4:7], v[196:199], v[188:191], v[4:7]
	v_mfma_f32_16x16x32_bf16 v[0:3], v[214:217], v[188:191], v[0:3]
	v_mfma_f32_16x16x32_bf16 v[52:55], v[210:213], v[168:171], v[52:55]
	v_mfma_f32_16x16x32_bf16 v[48:51], v[218:221], v[168:171], v[48:51]
	v_mfma_f32_16x16x32_bf16 v[36:39], v[210:213], v[176:179], v[36:39]
	v_mfma_f32_16x16x32_bf16 v[32:35], v[218:221], v[176:179], v[32:35]
	v_mfma_f32_16x16x32_bf16 v[20:23], v[210:213], v[184:187], v[20:23]
	v_mfma_f32_16x16x32_bf16 v[16:19], v[218:221], v[184:187], v[16:19]
	v_mfma_f32_16x16x32_bf16 v[4:7], v[210:213], v[192:195], v[4:7]
	v_mfma_f32_16x16x32_bf16 v[0:3], v[218:221], v[192:195], v[0:3]
	s_setprio 0
	s_add_i32 s75, s75, 2
	s_add_u32 s0, s0, 0x100
	s_addc_u32 s1, s1, 0
	s_add_u32 s38, s38, 0x100
	s_addc_u32 s39, s39, 0
	s_cmp_gt_u32 s75, 13
	s_barrier
	s_cbranch_scc0 .LBB0_242
	s_cmp_lt_u32 s21, 10
	s_cselect_b32 s1, 2, 3
	s_cmp_gt_u32 s21, 7
	s_cselect_b32 s1, s1, 4
	s_cmp_gt_u32 s21, 3
	s_cselect_b32 s1, s1, 1
	s_cmp_gt_i32 s21, 1
	s_cselect_b32 s7, s1, 0
	s_and_b32 s1, s21, -2
	s_and_b32 s22, s21, -4
	s_add_i32 s23, s21, 4
	s_lshl_b32 s21, s21, 1
	s_add_i32 s25, s21, -4
	s_cmp_eq_u32 s1, 8
	s_cselect_b64 s[36:37], -1, 0
	v_mov_b32_e32 v128, v202
	s_and_b64 s[4:5], s[36:37], exec
	s_cselect_b32 s1, s25, s21
	v_readfirstlane_b32 s0, v128
	s_cmp_eq_u32 s22, 4
	s_cselect_b32 s21, s23, s1
	s_lshr_b32 s1, s0, 1
	s_ashr_i32 s0, s0, 2
	s_andn2_b32 s0, s0, 63
	s_ashr_i32 s75, s21, 31
	s_and_b32 s22, s1, 0x60
	v_and_or_b32 v164, v128, 15, s0
	s_lshl_b32 s23, s24, 1
	s_mul_i32 s0, s24, 0x48
	s_mul_hi_i32 s1, s23, 36
	s_add_u32 s0, s0, s21
	s_addc_u32 s1, s1, s75
	s_lshl_b64 s[0:1], s[0:1], 15
	s_add_u32 s0, s70, s0
	s_addc_u32 s1, s71, s1
	s_lshl_b32 s22, s22, 1
	v_bfe_u32 v165, v128, 4, 2
	s_add_u32 s0, s0, s22
	s_addc_u32 s1, s1, 0
	v_lshlrev_b32_e32 v128, 4, v165
	v_lshlrev_b32_e32 v142, 7, v164
	v_lshl_add_u64 v[144:145], s[0:1], 0, v[128:129]
	v_ashrrev_i32_e32 v143, 31, v142
	v_cmp_eq_u32_e64 s[4:5], 0, v165
	v_lshl_add_u64 v[146:147], v[142:143], 1, v[144:145]
	s_cmp_lt_i32 s7, 3
	s_mov_b64 s[0:1], -1
	s_cbranch_scc1 .LBB0_249
	s_cmp_gt_i32 s7, 3
	s_cbranch_scc0 .LBB0_246
	v_and_b32_e32 v149, 0x7fffffff, v125
	v_and_b32_e32 v148, 0x7fffffff, v124
	v_pk_fma_f32 v[148:149], v[148:149], s[84:85], 1.0 op_sel_hi:[1,0,0]
	v_mov_b64_e32 v[150:151], s[88:89]
	v_rcp_f32_e32 v148, v148
	v_rcp_f32_e32 v149, v149
	v_pk_mul_f32 v[154:155], v[124:125], v[124:125]
	v_and_b32_e32 v157, 0x7fffffff, v127
	v_pk_mul_f32 v[154:155], v[154:155], s[96:97] op_sel_hi:[1,0]
	v_pk_fma_f32 v[152:153], v[148:149], s[86:87], v[150:151] op_sel_hi:[1,0,0]
	v_exp_f32_e32 v154, v154
	v_pk_fma_f32 v[152:153], v[148:149], v[152:153], s[90:91] op_sel_hi:[1,1,0]
	v_exp_f32_e32 v155, v155
	v_pk_fma_f32 v[152:153], v[148:149], v[152:153], s[92:93] op_sel_hi:[1,1,0]
	v_and_b32_e32 v156, 0x7fffffff, v126
	v_pk_fma_f32 v[152:153], v[148:149], v[152:153], s[94:95] op_sel_hi:[1,1,0]
	v_pk_fma_f32 v[156:157], v[156:157], s[84:85], 1.0 op_sel_hi:[1,0,0]
	v_pk_mul_f32 v[148:149], v[148:149], v[152:153]
	v_rcp_f32_e32 v156, v156
	v_rcp_f32_e32 v157, v157
	v_pk_mul_f32 v[148:149], v[154:155], v[148:149]
	v_cmp_gt_f32_e32 vcc, 0, v124
	v_pk_mul_f32 v[154:155], v[124:125], v[148:149]
	v_pk_fma_f32 v[148:149], v[124:125], v[148:149], v[124:125] neg_lo:[1,0,0] neg_hi:[1,0,0]
	v_pk_mul_f32 v[152:153], v[126:127], v[126:127]
	v_cndmask_b32_e32 v148, v148, v154, vcc
	v_cmp_gt_f32_e32 vcc, 0, v125
	v_pk_mul_f32 v[152:153], v[152:153], s[96:97] op_sel_hi:[1,0]
	v_and_b32_e32 v169, 0x7fffffff, v123
	v_cndmask_b32_e32 v149, v149, v155, vcc
	v_pk_fma_f32 v[154:155], v[156:157], s[86:87], v[150:151] op_sel_hi:[1,0,0]
	v_exp_f32_e32 v152, v152
	v_pk_fma_f32 v[154:155], v[156:157], v[154:155], s[90:91] op_sel_hi:[1,1,0]
	v_exp_f32_e32 v153, v153
	v_pk_fma_f32 v[154:155], v[156:157], v[154:155], s[92:93] op_sel_hi:[1,1,0]
	v_cmp_gt_f32_e32 vcc, 0, v126
	v_pk_fma_f32 v[154:155], v[156:157], v[154:155], s[94:95] op_sel_hi:[1,1,0]
	v_and_b32_e32 v168, 0x7fffffff, v122
	v_pk_mul_f32 v[154:155], v[156:157], v[154:155]
	v_and_b32_e32 v157, 0x7fffffff, v121
	v_and_b32_e32 v156, 0x7fffffff, v120
	v_pk_fma_f32 v[156:157], v[156:157], s[84:85], 1.0 op_sel_hi:[1,0,0]
	v_pk_mul_f32 v[152:153], v[152:153], v[154:155]
	v_rcp_f32_e32 v156, v156
	v_rcp_f32_e32 v157, v157
	v_pk_mul_f32 v[154:155], v[126:127], v[152:153]
	v_pk_fma_f32 v[152:153], v[126:127], v[152:153], v[126:127] neg_lo:[1,0,0] neg_hi:[1,0,0]
	v_pk_fma_f32 v[168:169], v[168:169], s[84:85], 1.0 op_sel_hi:[1,0,0]
	v_cndmask_b32_e32 v152, v152, v154, vcc
	v_cmp_gt_f32_e32 vcc, 0, v127
	v_rcp_f32_e32 v168, v168
	v_rcp_f32_e32 v169, v169
	v_cndmask_b32_e32 v153, v153, v155, vcc
	v_pk_fma_f32 v[154:155], v[156:157], s[86:87], v[150:151] op_sel_hi:[1,0,0]
	v_pk_mul_f32 v[166:167], v[120:121], v[120:121]
	v_pk_fma_f32 v[154:155], v[156:157], v[154:155], s[90:91] op_sel_hi:[1,1,0]
	v_pk_mul_f32 v[166:167], v[166:167], s[96:97] op_sel_hi:[1,0]
	v_pk_fma_f32 v[154:155], v[156:157], v[154:155], s[92:93] op_sel_hi:[1,1,0]
	v_exp_f32_e32 v166, v166
	v_pk_fma_f32 v[154:155], v[156:157], v[154:155], s[94:95] op_sel_hi:[1,1,0]
	v_exp_f32_e32 v167, v167
	v_pk_mul_f32 v[154:155], v[156:157], v[154:155]
	v_pk_mul_f32 v[156:157], v[122:123], v[122:123]
	v_pk_fma_f32 v[150:151], v[168:169], s[86:87], v[150:151] op_sel_hi:[1,0,0]
	v_pk_mul_f32 v[156:157], v[156:157], s[96:97] op_sel_hi:[1,0]
	v_pk_fma_f32 v[150:151], v[168:169], v[150:151], s[90:91] op_sel_hi:[1,1,0]
	v_exp_f32_e32 v156, v156
	v_exp_f32_e32 v157, v157
	v_pk_fma_f32 v[150:151], v[168:169], v[150:151], s[92:93] op_sel_hi:[1,1,0]
	v_pk_mul_f32 v[154:155], v[166:167], v[154:155]
	v_pk_fma_f32 v[150:151], v[168:169], v[150:151], s[94:95] op_sel_hi:[1,1,0]
	v_pk_mul_f32 v[166:167], v[120:121], v[154:155]
	v_pk_fma_f32 v[154:155], v[120:121], v[154:155], v[120:121] neg_lo:[1,0,0] neg_hi:[1,0,0]
	v_cmp_gt_f32_e32 vcc, 0, v120
	v_pk_mul_f32 v[150:151], v[168:169], v[150:151]
	v_mul_f32_e32 v128, 0xbfb8aa3b, v116
	v_cndmask_b32_e32 v154, v154, v166, vcc
	v_cmp_gt_f32_e32 vcc, 0, v121
	v_pk_mul_f32 v[150:151], v[156:157], v[150:151]
	v_exp_f32_e32 v128, v128
	v_cndmask_b32_e32 v155, v155, v167, vcc
	v_pk_mul_f32 v[156:157], v[122:123], v[150:151]
	v_pk_fma_f32 v[150:151], v[122:123], v[150:151], v[122:123] neg_lo:[1,0,0] neg_hi:[1,0,0]
	v_cmp_gt_f32_e32 vcc, 0, v122
	v_add_f32_e32 v128, 1.0, v128
	s_mov_b64 s[0:1], 0
	v_cndmask_b32_e32 v150, v150, v156, vcc
	v_mul_f32_e32 v156, 0xbfb8aa3b, v117
	v_exp_f32_e32 v166, v156
	v_cmp_gt_f32_e32 vcc, 0, v123
	v_rcp_f32_e32 v156, v128
	v_add_f32_e32 v128, 1.0, v166
	v_cndmask_b32_e32 v151, v151, v157, vcc
	v_mul_f32_e32 v157, 0xbfb8aa3b, v118
	v_exp_f32_e32 v166, v157
	v_mul_f32_e32 v157, 0xbfb8aa3b, v119
	v_exp_f32_e32 v167, v157
	v_rcp_f32_e32 v157, v128
	v_add_f32_e32 v128, 1.0, v166
	v_rcp_f32_e32 v166, v128
	v_add_f32_e32 v128, 1.0, v167
	v_mul_f32_e32 v167, 0xbfb8aa3b, v112
	v_exp_f32_e32 v168, v167
	v_mul_f32_e32 v167, 0xbfb8aa3b, v113
	v_exp_f32_e32 v169, v167
	v_rcp_f32_e32 v167, v128
	v_add_f32_e32 v128, 1.0, v168
	v_rcp_f32_e32 v168, v128
	v_add_f32_e32 v128, 1.0, v169
	v_mul_f32_e32 v169, 0xbfb8aa3b, v114
	v_exp_f32_e32 v170, v169
	v_mul_f32_e32 v169, 0xbfb8aa3b, v115
	v_exp_f32_e32 v171, v169
	v_rcp_f32_e32 v169, v128
	v_add_f32_e32 v128, 1.0, v170
	v_rcp_f32_e32 v170, v128
	v_add_f32_e32 v128, 1.0, v171
	v_rcp_f32_e32 v171, v128
	v_pk_mul_f32 v[156:157], v[116:117], v[156:157]
	v_pk_mul_f32 v[168:169], v[112:113], v[168:169]
	v_pk_mul_f32 v[166:167], v[118:119], v[166:167]
	v_pk_mul_f32 v[170:171], v[114:115], v[170:171]
	v_pk_mul_f32 v[148:149], v[148:149], v[156:157]
	v_pk_mul_f32 v[156:157], v[150:151], v[170:171]
	v_pk_mul_f32 v[150:151], v[154:155], v[168:169]
	v_pk_mul_f32 v[152:153], v[152:153], v[166:167]
	v_cvt_pk_bf16_f32 v148, v148, v149
	v_cvt_pk_bf16_f32 v150, v150, v151
	v_cvt_pk_bf16_f32 v151, v156, v157
	s_nop 0
	v_cvt_pk_bf16_f32 v149, v152, v153
	global_store_dwordx4 v[146:147], v[148:151], off

.LBB0_816:
	s_add_u32 s26, s36, s38
	ds_read_b128 v[134:137], v164
	ds_read_b128 v[138:141], v164 offset:1024
	ds_read_b128 v[142:145], v164 offset:2048
	ds_read_b128 v[170:173], v164 offset:3072
	s_addc_u32 s27, s37, s39
	s_add_u32 s26, s26, 0xcd48100
	s_addc_u32 s27, s27, 0
	s_add_u32 s56, s74, s38
	s_addc_u32 s57, s75, s39
	s_cmpk_eq_i32 s38, 0x300
	s_cselect_b32 s59, s15, s27
	s_cselect_b32 s58, s1, s26
	s_cselect_b32 s57, s33, s57
	s_cselect_b32 s56, s25, s56
	s_mov_b32 m0, s60
	v_lshl_add_u64 v[146:147], v[128:129], 0, s[38:39]
	ds_read_b128 v[174:177], v165
	ds_read_b128 v[178:181], v165 offset:1024
	ds_read_b128 v[182:185], v165 offset:2048
	ds_read_b128 v[186:189], v165 offset:3072
	ds_read_b128 v[190:193], v165 offset:4096
	ds_read_b128 v[194:197], v165 offset:5120
	ds_read_b128 v[198:201], v165 offset:6144
	ds_read_b128 v[210:213], v165 offset:7168
	global_load_lds_dwordx4 v[146:147], off
	v_lshl_add_u64 v[146:147], v[130:131], 0, s[38:39]
	s_mov_b32 m0, s61
	s_nop 0
	global_load_lds_dwordx4 v[146:147], off
	s_waitcnt lgkmcnt(8)
	s_waitcnt vmcnt(10)
	s_barrier
	s_waitcnt lgkmcnt(0)
	s_setprio 1
	s_waitcnt lgkmcnt(0)
	v_mfma_f32_16x16x32_bf16 v[124:127], v[134:137], v[174:177], v[124:127]
	v_mfma_f32_16x16x32_bf16 v[120:123], v[142:145], v[174:177], v[120:123]
	v_mfma_f32_16x16x32_bf16 v[116:119], v[134:137], v[182:185], v[116:119]
	v_mfma_f32_16x16x32_bf16 v[112:115], v[142:145], v[182:185], v[112:115]
	v_mfma_f32_16x16x32_bf16 v[100:103], v[134:137], v[190:193], v[100:103]
	v_mfma_f32_16x16x32_bf16 v[92:95], v[142:145], v[190:193], v[92:95]
	v_mfma_f32_16x16x32_bf16 v[84:87], v[134:137], v[198:201], v[84:87]
	v_mfma_f32_16x16x32_bf16 v[76:79], v[142:145], v[198:201], v[76:79]
	v_mfma_f32_16x16x32_bf16 v[124:127], v[138:141], v[178:181], v[124:127]
	v_mfma_f32_16x16x32_bf16 v[120:123], v[170:173], v[178:181], v[120:123]
	v_mfma_f32_16x16x32_bf16 v[116:119], v[138:141], v[186:189], v[116:119]
	v_mfma_f32_16x16x32_bf16 v[112:115], v[170:173], v[186:189], v[112:115]
	v_mfma_f32_16x16x32_bf16 v[100:103], v[138:141], v[194:197], v[100:103]
	v_mfma_f32_16x16x32_bf16 v[92:95], v[170:173], v[194:197], v[92:95]
	v_mfma_f32_16x16x32_bf16 v[84:87], v[138:141], v[210:213], v[84:87]
	v_mfma_f32_16x16x32_bf16 v[76:79], v[170:173], v[210:213], v[76:79]
	s_setprio 0
	s_barrier
	s_mov_b32 m0, s62
	v_lshl_add_u64 v[146:147], s[56:57], 0, v[150:151]
	ds_read_b128 v[214:217], v166
	ds_read_b128 v[218:221], v166 offset:1024
	ds_read_b128 v[222:225], v166 offset:2048
	ds_read_b128 v[226:229], v166 offset:3072
	global_load_lds_dwordx4 v[146:147], off
	v_lshl_add_u64 v[160:161], s[56:57], 0, v[154:155]
	s_mov_b32 m0, s63
	s_nop 0
	global_load_lds_dwordx4 v[160:161], off
	s_waitcnt vmcnt(10)
	s_barrier
	s_waitcnt lgkmcnt(0)
	s_setprio 1
	s_waitcnt lgkmcnt(0)
	v_mfma_f32_16x16x32_bf16 v[108:111], v[214:217], v[174:177], v[108:111]
	v_mfma_f32_16x16x32_bf16 v[104:107], v[222:225], v[174:177], v[104:107]
	v_mfma_f32_16x16x32_bf16 v[96:99], v[214:217], v[182:185], v[96:99]
	v_mfma_f32_16x16x32_bf16 v[88:91], v[222:225], v[182:185], v[88:91]
	v_mfma_f32_16x16x32_bf16 v[80:83], v[214:217], v[190:193], v[80:83]
	v_mfma_f32_16x16x32_bf16 v[72:75], v[222:225], v[190:193], v[72:75]
	v_mfma_f32_16x16x32_bf16 v[68:71], v[214:217], v[198:201], v[68:71]
	v_mfma_f32_16x16x32_bf16 v[64:67], v[222:225], v[198:201], v[64:67]
	v_mfma_f32_16x16x32_bf16 v[108:111], v[218:221], v[178:181], v[108:111]
	v_mfma_f32_16x16x32_bf16 v[104:107], v[226:229], v[178:181], v[104:107]
	v_mfma_f32_16x16x32_bf16 v[96:99], v[218:221], v[186:189], v[96:99]
	v_mfma_f32_16x16x32_bf16 v[88:91], v[226:229], v[186:189], v[88:91]
	v_mfma_f32_16x16x32_bf16 v[80:83], v[218:221], v[194:197], v[80:83]
	v_mfma_f32_16x16x32_bf16 v[72:75], v[226:229], v[194:197], v[72:75]
	v_mfma_f32_16x16x32_bf16 v[68:71], v[218:221], v[210:213], v[68:71]
	v_mfma_f32_16x16x32_bf16 v[64:67], v[226:229], v[210:213], v[64:67]
	s_setprio 0
	s_mov_b32 m0, s19
	v_lshl_add_u64 v[230:231], s[58:59], 0, v[148:149]
	s_barrier
	ds_read_b128 v[174:177], v165 offset:16384
	ds_read_b128 v[178:181], v165 offset:17408
	ds_read_b128 v[182:185], v165 offset:18432
	ds_read_b128 v[186:189], v165 offset:19456
	ds_read_b128 v[190:193], v165 offset:20480
	ds_read_b128 v[194:197], v165 offset:21504
	ds_read_b128 v[198:201], v165 offset:22528
	ds_read_b128 v[210:213], v165 offset:23552
	global_load_lds_dwordx4 v[230:231], off
	v_lshl_add_u64 v[232:233], s[58:59], 0, v[152:153]
	s_mov_b32 m0, s20
	s_nop 0
	global_load_lds_dwordx4 v[232:233], off
	s_barrier
	s_waitcnt lgkmcnt(0)
	s_setprio 1
	s_waitcnt lgkmcnt(0)
	v_mfma_f32_16x16x32_bf16 v[60:63], v[134:137], v[174:177], v[60:63]
	v_mfma_f32_16x16x32_bf16 v[56:59], v[142:145], v[174:177], v[56:59]
	v_mfma_f32_16x16x32_bf16 v[48:51], v[134:137], v[182:185], v[48:51]
	v_mfma_f32_16x16x32_bf16 v[40:43], v[142:145], v[182:185], v[40:43]
	v_mfma_f32_16x16x32_bf16 v[32:35], v[134:137], v[190:193], v[32:35]
	v_mfma_f32_16x16x32_bf16 v[24:27], v[142:145], v[190:193], v[24:27]
	v_mfma_f32_16x16x32_bf16 v[16:19], v[134:137], v[198:201], v[16:19]
	v_mfma_f32_16x16x32_bf16 v[8:11], v[142:145], v[198:201], v[8:11]
	v_mfma_f32_16x16x32_bf16 v[60:63], v[138:141], v[178:181], v[60:63]
	v_mfma_f32_16x16x32_bf16 v[56:59], v[170:173], v[178:181], v[56:59]
	v_mfma_f32_16x16x32_bf16 v[48:51], v[138:141], v[186:189], v[48:51]
	v_mfma_f32_16x16x32_bf16 v[40:43], v[170:173], v[186:189], v[40:43]
	v_mfma_f32_16x16x32_bf16 v[32:35], v[138:141], v[194:197], v[32:35]
	v_mfma_f32_16x16x32_bf16 v[24:27], v[170:173], v[194:197], v[24:27]
	v_mfma_f32_16x16x32_bf16 v[16:19], v[138:141], v[210:213], v[16:19]
	v_mfma_f32_16x16x32_bf16 v[8:11], v[170:173], v[210:213], v[8:11]
	s_setprio 0
	s_barrier
	s_add_u32 s82, s56, 0x40000
	s_addc_u32 s83, s57, 0
	s_mov_b32 m0, s64
	v_lshl_add_u64 v[134:135], s[82:83], 0, v[150:151]
	global_load_lds_dwordx4 v[134:135], off
	v_lshl_add_u64 v[134:135], s[82:83], 0, v[154:155]
	s_mov_b32 m0, s65
	s_nop 0
	global_load_lds_dwordx4 v[134:135], off
	s_waitcnt vmcnt(10)
	s_barrier
	s_setprio 1
	v_mfma_f32_16x16x32_bf16 v[52:55], v[214:217], v[174:177], v[52:55]
	v_mfma_f32_16x16x32_bf16 v[44:47], v[222:225], v[174:177], v[44:47]
	v_mfma_f32_16x16x32_bf16 v[36:39], v[214:217], v[182:185], v[36:39]
	v_mfma_f32_16x16x32_bf16 v[28:31], v[222:225], v[182:185], v[28:31]
	v_mfma_f32_16x16x32_bf16 v[20:23], v[214:217], v[190:193], v[20:23]
	v_mfma_f32_16x16x32_bf16 v[12:15], v[222:225], v[190:193], v[12:15]
	v_mfma_f32_16x16x32_bf16 v[4:7], v[214:217], v[198:201], v[4:7]
	v_mfma_f32_16x16x32_bf16 v[0:3], v[222:225], v[198:201], v[0:3]
	v_mfma_f32_16x16x32_bf16 v[52:55], v[218:221], v[178:181], v[52:55]
	v_mfma_f32_16x16x32_bf16 v[44:47], v[226:229], v[178:181], v[44:47]
	v_mfma_f32_16x16x32_bf16 v[36:39], v[218:221], v[186:189], v[36:39]
	v_mfma_f32_16x16x32_bf16 v[28:31], v[226:229], v[186:189], v[28:31]
	v_mfma_f32_16x16x32_bf16 v[20:23], v[218:221], v[194:197], v[20:23]
	v_mfma_f32_16x16x32_bf16 v[12:15], v[226:229], v[194:197], v[12:15]
	v_mfma_f32_16x16x32_bf16 v[4:7], v[218:221], v[210:213], v[4:7]
	v_mfma_f32_16x16x32_bf16 v[0:3], v[226:229], v[210:213], v[0:3]
	s_setprio 0
	s_barrier
	ds_read_b128 v[134:137], v167
	ds_read_b128 v[138:141], v167 offset:1024
	ds_read_b128 v[142:145], v167 offset:2048
	ds_read_b128 v[170:173], v167 offset:3072
	s_add_u32 s58, s58, 0x40000
	s_addc_u32 s59, s59, 0
	s_mov_b32 m0, s21
	v_lshl_add_u64 v[214:215], s[58:59], 0, v[148:149]
	ds_read_b128 v[174:177], v165 offset:32768
	ds_read_b128 v[178:181], v165 offset:33792
	ds_read_b128 v[182:185], v165 offset:34816
	ds_read_b128 v[186:189], v165 offset:35840
	ds_read_b128 v[190:193], v165 offset:36864
	ds_read_b128 v[194:197], v165 offset:37888
	ds_read_b128 v[198:201], v165 offset:38912
	ds_read_b128 v[210:213], v165 offset:39936
	global_load_lds_dwordx4 v[214:215], off
	v_lshl_add_u64 v[214:215], s[58:59], 0, v[152:153]
	s_mov_b32 m0, s22
	s_nop 0
	global_load_lds_dwordx4 v[214:215], off
	s_waitcnt lgkmcnt(8)
	s_waitcnt vmcnt(10)
	s_barrier
	s_waitcnt lgkmcnt(0)
	s_setprio 1
	s_waitcnt lgkmcnt(0)
	v_mfma_f32_16x16x32_bf16 v[124:127], v[134:137], v[174:177], v[124:127]
	v_mfma_f32_16x16x32_bf16 v[120:123], v[142:145], v[174:177], v[120:123]
	v_mfma_f32_16x16x32_bf16 v[116:119], v[134:137], v[182:185], v[116:119]
	v_mfma_f32_16x16x32_bf16 v[112:115], v[142:145], v[182:185], v[112:115]
	v_mfma_f32_16x16x32_bf16 v[100:103], v[134:137], v[190:193], v[100:103]
	v_mfma_f32_16x16x32_bf16 v[92:95], v[142:145], v[190:193], v[92:95]
	v_mfma_f32_16x16x32_bf16 v[84:87], v[134:137], v[198:201], v[84:87]
	v_mfma_f32_16x16x32_bf16 v[76:79], v[142:145], v[198:201], v[76:79]
	v_mfma_f32_16x16x32_bf16 v[124:127], v[138:141], v[178:181], v[124:127]
	v_mfma_f32_16x16x32_bf16 v[120:123], v[170:173], v[178:181], v[120:123]
	v_mfma_f32_16x16x32_bf16 v[116:119], v[138:141], v[186:189], v[116:119]
	v_mfma_f32_16x16x32_bf16 v[112:115], v[170:173], v[186:189], v[112:115]
	v_mfma_f32_16x16x32_bf16 v[100:103], v[138:141], v[194:197], v[100:103]
	v_mfma_f32_16x16x32_bf16 v[92:95], v[170:173], v[194:197], v[92:95]
	v_mfma_f32_16x16x32_bf16 v[84:87], v[138:141], v[210:213], v[84:87]
	v_mfma_f32_16x16x32_bf16 v[76:79], v[170:173], v[210:213], v[76:79]
	s_setprio 0
	s_barrier
	s_mov_b32 m0, s66
	v_lshl_add_u64 v[146:147], v[146:147], 0, s[16:17]
	ds_read_b128 v[214:217], v168
	ds_read_b128 v[218:221], v168 offset:1024
	ds_read_b128 v[222:225], v168 offset:2048
	ds_read_b128 v[226:229], v168 offset:3072
	global_load_lds_dwordx4 v[146:147], off
	v_lshl_add_u64 v[146:147], v[160:161], 0, s[16:17]
	s_mov_b32 m0, s67
	s_nop 0
	global_load_lds_dwordx4 v[146:147], off
	s_waitcnt vmcnt(10)
	s_barrier
	s_waitcnt lgkmcnt(0)
	s_setprio 1
	s_waitcnt lgkmcnt(0)
	v_mfma_f32_16x16x32_bf16 v[108:111], v[214:217], v[174:177], v[108:111]
	v_mfma_f32_16x16x32_bf16 v[104:107], v[222:225], v[174:177], v[104:107]
	v_mfma_f32_16x16x32_bf16 v[96:99], v[214:217], v[182:185], v[96:99]
	v_mfma_f32_16x16x32_bf16 v[88:91], v[222:225], v[182:185], v[88:91]
	v_mfma_f32_16x16x32_bf16 v[80:83], v[214:217], v[190:193], v[80:83]
	v_mfma_f32_16x16x32_bf16 v[72:75], v[222:225], v[190:193], v[72:75]
	v_mfma_f32_16x16x32_bf16 v[68:71], v[214:217], v[198:201], v[68:71]
	v_mfma_f32_16x16x32_bf16 v[64:67], v[222:225], v[198:201], v[64:67]
	v_mfma_f32_16x16x32_bf16 v[108:111], v[218:221], v[178:181], v[108:111]
	v_mfma_f32_16x16x32_bf16 v[104:107], v[226:229], v[178:181], v[104:107]
	v_mfma_f32_16x16x32_bf16 v[96:99], v[218:221], v[186:189], v[96:99]
	v_mfma_f32_16x16x32_bf16 v[88:91], v[226:229], v[186:189], v[88:91]
	v_mfma_f32_16x16x32_bf16 v[80:83], v[218:221], v[194:197], v[80:83]
	v_mfma_f32_16x16x32_bf16 v[72:75], v[226:229], v[194:197], v[72:75]
	v_mfma_f32_16x16x32_bf16 v[68:71], v[218:221], v[210:213], v[68:71]
	v_mfma_f32_16x16x32_bf16 v[64:67], v[226:229], v[210:213], v[64:67]
	s_setprio 0
	s_mov_b32 m0, s23
	v_lshl_add_u64 v[146:147], v[230:231], 0, s[16:17]
	s_barrier
	ds_read_b128 v[174:177], v165 offset:49152
	ds_read_b128 v[178:181], v165 offset:50176
	ds_read_b128 v[182:185], v165 offset:51200
	ds_read_b128 v[186:189], v165 offset:52224
	ds_read_b128 v[190:193], v165 offset:53248
	ds_read_b128 v[194:197], v165 offset:54272
	ds_read_b128 v[198:201], v165 offset:55296
	ds_read_b128 v[210:213], v165 offset:56320
	global_load_lds_dwordx4 v[146:147], off
	v_lshl_add_u64 v[146:147], v[232:233], 0, s[16:17]
	s_mov_b32 m0, s24
	s_nop 0
	global_load_lds_dwordx4 v[146:147], off
	s_barrier
	s_waitcnt lgkmcnt(0)
	s_setprio 1
	s_waitcnt lgkmcnt(0)
	v_mfma_f32_16x16x32_bf16 v[60:63], v[134:137], v[174:177], v[60:63]
	v_mfma_f32_16x16x32_bf16 v[56:59], v[142:145], v[174:177], v[56:59]
	v_mfma_f32_16x16x32_bf16 v[48:51], v[134:137], v[182:185], v[48:51]
	v_mfma_f32_16x16x32_bf16 v[40:43], v[142:145], v[182:185], v[40:43]
	v_mfma_f32_16x16x32_bf16 v[32:35], v[134:137], v[190:193], v[32:35]
	v_mfma_f32_16x16x32_bf16 v[24:27], v[142:145], v[190:193], v[24:27]
	v_mfma_f32_16x16x32_bf16 v[16:19], v[134:137], v[198:201], v[16:19]
	v_mfma_f32_16x16x32_bf16 v[8:11], v[142:145], v[198:201], v[8:11]
	v_mfma_f32_16x16x32_bf16 v[60:63], v[138:141], v[178:181], v[60:63]
	v_mfma_f32_16x16x32_bf16 v[56:59], v[170:173], v[178:181], v[56:59]
	v_mfma_f32_16x16x32_bf16 v[48:51], v[138:141], v[186:189], v[48:51]
	v_mfma_f32_16x16x32_bf16 v[40:43], v[170:173], v[186:189], v[40:43]
	v_mfma_f32_16x16x32_bf16 v[32:35], v[138:141], v[194:197], v[32:35]
	v_mfma_f32_16x16x32_bf16 v[24:27], v[170:173], v[194:197], v[24:27]
	v_mfma_f32_16x16x32_bf16 v[16:19], v[138:141], v[210:213], v[16:19]
	v_mfma_f32_16x16x32_bf16 v[8:11], v[170:173], v[210:213], v[8:11]
	s_setprio 0
	s_barrier
	s_add_u32 s56, s56, 0x40080
	s_addc_u32 s57, s57, 0
	s_mov_b32 m0, s68
	v_lshl_add_u64 v[134:135], s[56:57], 0, v[150:151]
	global_load_lds_dwordx4 v[134:135], off
	v_lshl_add_u64 v[134:135], s[56:57], 0, v[154:155]
	s_mov_b32 m0, s69
	s_nop 0
	global_load_lds_dwordx4 v[134:135], off
	s_waitcnt vmcnt(10)
	s_barrier
	s_setprio 1
	v_mfma_f32_16x16x32_bf16 v[52:55], v[214:217], v[174:177], v[52:55]
	v_mfma_f32_16x16x32_bf16 v[44:47], v[222:225], v[174:177], v[44:47]
	v_mfma_f32_16x16x32_bf16 v[36:39], v[214:217], v[182:185], v[36:39]
	v_mfma_f32_16x16x32_bf16 v[28:31], v[222:225], v[182:185], v[28:31]
	v_mfma_f32_16x16x32_bf16 v[20:23], v[214:217], v[190:193], v[20:23]
	v_mfma_f32_16x16x32_bf16 v[12:15], v[222:225], v[190:193], v[12:15]
	v_mfma_f32_16x16x32_bf16 v[4:7], v[214:217], v[198:201], v[4:7]
	v_mfma_f32_16x16x32_bf16 v[0:3], v[222:225], v[198:201], v[0:3]
	v_mfma_f32_16x16x32_bf16 v[52:55], v[218:221], v[178:181], v[52:55]
	v_mfma_f32_16x16x32_bf16 v[44:47], v[226:229], v[178:181], v[44:47]
	v_mfma_f32_16x16x32_bf16 v[36:39], v[218:221], v[186:189], v[36:39]
	v_mfma_f32_16x16x32_bf16 v[28:31], v[226:229], v[186:189], v[28:31]
	v_mfma_f32_16x16x32_bf16 v[20:23], v[218:221], v[194:197], v[20:23]
	v_mfma_f32_16x16x32_bf16 v[12:15], v[226:229], v[194:197], v[12:15]
	v_mfma_f32_16x16x32_bf16 v[4:7], v[218:221], v[210:213], v[4:7]
	v_mfma_f32_16x16x32_bf16 v[0:3], v[226:229], v[210:213], v[0:3]
	s_setprio 0
	s_add_i32 s80, s80, 2
	s_add_u32 s38, s38, 0x100
	s_addc_u32 s39, s39, 0
	s_cmp_gt_u32 s80, 5
	s_barrier
	s_cbranch_scc0 .LBB0_816
	s_sext_i32_i8 s4, s4
	s_mul_i32 s8, s8, 0x240000
	s_lshl_b32 s4, s4, 17
	v_or3_b32 v128, s18, v132, v163
	s_add_i32 s4, s8, s4
	v_lshlrev_b32_e32 v169, 1, v128
	s_add_i32 s4, s4, 0xa0000
	v_add_u32_e32 v132, s4, v169
	v_mov_b32_e32 v133, 0
	s_mov_b32 s4, 0x10000
	v_lshl_add_u64 v[160:161], s[70:71], 0, v[132:133]
	global_load_dwordx4 v[128:131], v132, s[70:71]
	v_add_co_u32_e32 v132, vcc, s4, v160
	s_mov_b32 s4, 0x123000
	s_nop 0
	v_addc_co_u32_e32 v133, vcc, 0, v161, vcc
	v_add_co_u32_e32 v136, vcc, 0x1000, v160
	global_load_dwordx4 v[132:135], v[132:133], off
	s_nop 0
	v_addc_co_u32_e32 v137, vcc, 0, v161, vcc
	global_load_dwordx4 v[144:147], v[136:137], off
	v_add_co_u32_e32 v136, vcc, 0x11000, v160
	s_mov_b32 s8, 0x120000
	s_nop 0
	v_addc_co_u32_e32 v137, vcc, 0, v161, vcc
	global_load_dwordx4 v[140:143], v[136:137], off
	v_add_co_u32_e32 v136, vcc, 0x2000, v160
	s_add_u32 s2, s78, s2
	s_nop 0
	v_addc_co_u32_e32 v137, vcc, 0, v161, vcc
	global_load_dwordx4 v[170:173], v[136:137], off
	v_add_co_u32_e32 v136, vcc, s4, v160
	s_mov_b32 s4, 0x131000
	s_nop 0
	v_addc_co_u32_e32 v137, vcc, 0, v161, vcc
	v_add_co_u32_e32 v174, vcc, s8, v160
	s_addc_u32 s3, s79, s3
	s_nop 0
	v_addc_co_u32_e32 v175, vcc, 0, v161, vcc
	v_add_co_u32_e32 v178, vcc, 0x12000, v160
	global_load_dwordx4 v[136:139], v[136:137], off
	s_nop 0
	global_load_dwordx4 v[174:177], v[174:175], off
	v_addc_co_u32_e32 v179, vcc, 0, v161, vcc
	v_add_co_u32_e32 v182, vcc, 0x3000, v160
	global_load_dwordx4 v[178:181], v[178:179], off
	s_nop 0
	v_addc_co_u32_e32 v183, vcc, 0, v161, vcc
	v_add_co_u32_e32 v186, vcc, 0x13000, v160
	s_add_u32 s38, s2, 0x36c8500
	s_nop 0
	v_addc_co_u32_e32 v187, vcc, 0, v161, vcc
	global_load_dwordx4 v[182:185], v[182:183], off
	s_nop 0
	global_load_dwordx4 v[186:189], v[186:187], off
	s_addc_u32 s39, s3, 0
	s_sub_i32 s2, s5, s73
	s_lshl_b32 s3, s72, 5
	s_sub_i32 s2, s2, s3
	s_sext_i32_i8 s2, s2
	s_add_i32 s2, s9, s2
	s_ashr_i32 s3, s2, 31
	s_lshl_b64 s[2:3], s[2:3], 19
	s_add_u32 s2, s78, s2
	s_addc_u32 s3, s79, s3
	s_mov_b32 s56, -2
	s_mov_b64 s[8:9], 0x80
	s_waitcnt vmcnt(0)
	v_lshlrev_b32_e32 v190, 16, v128
	v_and_b32_e32 v191, 0xffff0000, v128
	v_lshlrev_b32_e32 v128, 16, v129
	v_and_b32_e32 v129, 0xffff0000, v129
	v_lshlrev_b32_e32 v192, 16, v130
	v_and_b32_e32 v193, 0xffff0000, v130
	v_lshlrev_b32_e32 v130, 16, v131
	v_and_b32_e32 v131, 0xffff0000, v131
	v_pk_mul_f32 v[126:127], v[126:127], v[128:129]
	v_pk_mul_f32 v[122:123], v[122:123], v[130:131]
	v_lshlrev_b32_e32 v128, 16, v132
	v_and_b32_e32 v129, 0xffff0000, v132
	v_lshlrev_b32_e32 v130, 16, v133
	v_and_b32_e32 v131, 0xffff0000, v133
	v_lshlrev_b32_e32 v132, 16, v134
	v_and_b32_e32 v133, 0xffff0000, v134
	v_pk_mul_f32 v[132:133], v[104:105], v[132:133]
	v_lshlrev_b32_e32 v104, 16, v144
	v_and_b32_e32 v105, 0xffff0000, v144
	v_pk_mul_f32 v[124:125], v[124:125], v[190:191]
	v_lshlrev_b32_e32 v134, 16, v135
	v_and_b32_e32 v135, 0xffff0000, v135
	v_pk_mul_f32 v[116:117], v[116:117], v[104:105]
	v_lshlrev_b32_e32 v104, 16, v146
	v_and_b32_e32 v105, 0xffff0000, v146
	v_add_co_u32_e32 v190, vcc, s4, v160
	v_pk_mul_f32 v[134:135], v[106:107], v[134:135]
	v_lshlrev_b32_e32 v106, 16, v145
	v_and_b32_e32 v107, 0xffff0000, v145
	v_pk_mul_f32 v[112:113], v[112:113], v[104:105]
	v_lshlrev_b32_e32 v104, 16, v140
	v_and_b32_e32 v105, 0xffff0000, v140
	v_addc_co_u32_e32 v191, vcc, 0, v161, vcc
	s_mov_b32 s4, 0x122000
	v_pk_mul_f32 v[120:121], v[120:121], v[192:193]
	v_pk_mul_f32 v[118:119], v[118:119], v[106:107]
	v_lshlrev_b32_e32 v106, 16, v147
	v_and_b32_e32 v107, 0xffff0000, v147
	v_pk_mul_f32 v[104:105], v[96:97], v[104:105]
	v_lshlrev_b32_e32 v96, 16, v142
	v_and_b32_e32 v97, 0xffff0000, v142
	global_load_dwordx4 v[144:147], v[190:191], off offset:-4096
	v_add_co_u32_e32 v192, vcc, s4, v160
	v_pk_mul_f32 v[128:129], v[108:109], v[128:129]
	v_pk_mul_f32 v[114:115], v[114:115], v[106:107]
	v_lshlrev_b32_e32 v106, 16, v141
	v_and_b32_e32 v107, 0xffff0000, v141
	v_pk_mul_f32 v[108:109], v[88:89], v[96:97]
	v_lshlrev_b32_e32 v88, 16, v170
	v_and_b32_e32 v89, 0xffff0000, v170
	v_addc_co_u32_e32 v193, vcc, 0, v161, vcc
	v_pk_mul_f32 v[106:107], v[98:99], v[106:107]
	v_lshlrev_b32_e32 v98, 16, v143
	v_and_b32_e32 v99, 0xffff0000, v143
	global_load_dwordx4 v[140:143], v[192:193], off offset:-4096
	v_pk_mul_f32 v[96:97], v[100:101], v[88:89]
	v_lshlrev_b32_e32 v88, 16, v172
	v_and_b32_e32 v89, 0xffff0000, v172
	v_pk_mul_f32 v[130:131], v[110:111], v[130:131]
	v_pk_mul_f32 v[110:111], v[90:91], v[98:99]
	v_lshlrev_b32_e32 v90, 16, v171
	v_and_b32_e32 v91, 0xffff0000, v171
	v_pk_mul_f32 v[100:101], v[92:93], v[88:89]
	v_lshlrev_b32_e32 v88, 16, v178
	v_and_b32_e32 v89, 0xffff0000, v178
	v_pk_mul_f32 v[98:99], v[102:103], v[90:91]
	v_lshlrev_b32_e32 v90, 16, v173
	v_and_b32_e32 v91, 0xffff0000, v173
	global_load_dwordx4 v[170:173], v[190:191], off
	v_pk_mul_f32 v[88:89], v[80:81], v[88:89]
	v_lshlrev_b32_e32 v80, 16, v180
	v_and_b32_e32 v81, 0xffff0000, v180
	v_pk_mul_f32 v[102:103], v[94:95], v[90:91]
	v_lshlrev_b32_e32 v90, 16, v179
	v_and_b32_e32 v91, 0xffff0000, v179
	v_pk_mul_f32 v[92:93], v[72:73], v[80:81]
	v_lshlrev_b32_e32 v72, 16, v182
	v_and_b32_e32 v73, 0xffff0000, v182
	s_mov_b32 s4, 0x133000
	v_pk_mul_f32 v[90:91], v[82:83], v[90:91]
	v_lshlrev_b32_e32 v82, 16, v181
	v_and_b32_e32 v83, 0xffff0000, v181
	global_load_dwordx4 v[178:181], v[192:193], off
	v_pk_mul_f32 v[80:81], v[84:85], v[72:73]
	v_add_co_u32_e32 v84, vcc, s4, v160
	v_pk_mul_f32 v[94:95], v[74:75], v[82:83]
	s_nop 0
	v_addc_co_u32_e32 v85, vcc, 0, v161, vcc
	global_load_dwordx4 v[190:193], v[84:85], off offset:-4096
	v_lshlrev_b32_e32 v74, 16, v183
	v_and_b32_e32 v75, 0xffff0000, v183
	v_pk_mul_f32 v[82:83], v[86:87], v[74:75]
	global_load_dwordx4 v[84:87], v[84:85], off
	v_lshlrev_b32_e32 v72, 16, v184
	v_and_b32_e32 v73, 0xffff0000, v184
	v_lshlrev_b32_e32 v74, 16, v185
	v_and_b32_e32 v75, 0xffff0000, v185
	v_pk_mul_f32 v[78:79], v[78:79], v[74:75]
	v_pk_mul_f32 v[76:77], v[76:77], v[72:73]
	v_lshlrev_b32_e32 v72, 16, v186
	v_and_b32_e32 v73, 0xffff0000, v186
	v_lshlrev_b32_e32 v74, 16, v187
	v_and_b32_e32 v75, 0xffff0000, v187
	v_pk_mul_f32 v[70:71], v[70:71], v[74:75]
	v_pk_mul_f32 v[68:69], v[68:69], v[72:73]
	v_lshlrev_b32_e32 v72, 16, v188
	v_and_b32_e32 v73, 0xffff0000, v188
	v_lshlrev_b32_e32 v74, 16, v189
	v_and_b32_e32 v75, 0xffff0000, v189
	v_pk_mul_f32 v[74:75], v[66:67], v[74:75]
	v_pk_mul_f32 v[72:73], v[64:65], v[72:73]
	v_lshlrev_b32_e32 v64, 16, v174
	v_and_b32_e32 v65, 0xffff0000, v174
	v_lshlrev_b32_e32 v66, 16, v175
	v_and_b32_e32 v67, 0xffff0000, v175
	v_pk_mul_f32 v[62:63], v[62:63], v[66:67]
	v_pk_mul_f32 v[60:61], v[60:61], v[64:65]
	v_lshlrev_b32_e32 v64, 16, v176
	v_and_b32_e32 v65, 0xffff0000, v176
	v_lshlrev_b32_e32 v66, 16, v177
	v_and_b32_e32 v67, 0xffff0000, v177
	v_pk_mul_f32 v[66:67], v[58:59], v[66:67]
	v_pk_mul_f32 v[64:65], v[56:57], v[64:65]
	s_waitcnt vmcnt(0)
	v_lshlrev_b32_e32 v56, 16, v144
	v_and_b32_e32 v57, 0xffff0000, v144
	v_lshlrev_b32_e32 v58, 16, v145
	v_and_b32_e32 v59, 0xffff0000, v145
	v_pk_mul_f32 v[54:55], v[54:55], v[58:59]
	v_pk_mul_f32 v[52:53], v[52:53], v[56:57]
	v_lshlrev_b32_e32 v56, 16, v146
	v_and_b32_e32 v57, 0xffff0000, v146
	v_lshlrev_b32_e32 v58, 16, v147
	v_and_b32_e32 v59, 0xffff0000, v147
	v_pk_mul_f32 v[58:59], v[46:47], v[58:59]
	v_pk_mul_f32 v[56:57], v[44:45], v[56:57]
	v_lshlrev_b32_e32 v44, 16, v140
	v_and_b32_e32 v45, 0xffff0000, v140
	v_lshlrev_b32_e32 v46, 16, v141
	v_and_b32_e32 v47, 0xffff0000, v141
	v_pk_mul_f32 v[46:47], v[50:51], v[46:47]
	v_pk_mul_f32 v[44:45], v[48:49], v[44:45]
	v_lshlrev_b32_e32 v48, 16, v142
	v_and_b32_e32 v49, 0xffff0000, v142
	v_lshlrev_b32_e32 v50, 16, v143
	v_and_b32_e32 v51, 0xffff0000, v143
	v_pk_mul_f32 v[50:51], v[42:43], v[50:51]
	v_pk_mul_f32 v[48:49], v[40:41], v[48:49]
	v_lshlrev_b32_e32 v40, 16, v170
	v_and_b32_e32 v41, 0xffff0000, v170
	v_lshlrev_b32_e32 v42, 16, v171
	v_and_b32_e32 v43, 0xffff0000, v171
	v_pk_mul_f32 v[38:39], v[38:39], v[42:43]
	v_pk_mul_f32 v[36:37], v[36:37], v[40:41]
	v_lshlrev_b32_e32 v40, 16, v172
	v_and_b32_e32 v41, 0xffff0000, v172
	v_lshlrev_b32_e32 v42, 16, v173
	v_and_b32_e32 v43, 0xffff0000, v173
	v_pk_mul_f32 v[42:43], v[30:31], v[42:43]
	v_pk_mul_f32 v[40:41], v[28:29], v[40:41]
	s_mov_b64 s[4:5], 0xcd88480
	v_lshlrev_b32_e32 v28, 16, v178
	v_and_b32_e32 v29, 0xffff0000, v178
	v_lshlrev_b32_e32 v30, 16, v179
	v_and_b32_e32 v31, 0xffff0000, v179
	v_pk_mul_f32 v[30:31], v[34:35], v[30:31]
	v_pk_mul_f32 v[28:29], v[32:33], v[28:29]
	v_lshlrev_b32_e32 v32, 16, v180
	v_and_b32_e32 v33, 0xffff0000, v180
	v_lshlrev_b32_e32 v34, 16, v181
	v_and_b32_e32 v35, 0xffff0000, v181
	v_pk_mul_f32 v[34:35], v[26:27], v[34:35]
	v_pk_mul_f32 v[32:33], v[24:25], v[32:33]
	v_lshlrev_b32_e32 v24, 16, v190
	v_and_b32_e32 v25, 0xffff0000, v190
	v_lshlrev_b32_e32 v26, 16, v191
	v_and_b32_e32 v27, 0xffff0000, v191
	v_pk_mul_f32 v[22:23], v[22:23], v[26:27]
	v_pk_mul_f32 v[20:21], v[20:21], v[24:25]
	v_lshlrev_b32_e32 v24, 16, v192
	v_and_b32_e32 v25, 0xffff0000, v192
	v_lshlrev_b32_e32 v26, 16, v193
	v_and_b32_e32 v27, 0xffff0000, v193
	v_pk_mul_f32 v[26:27], v[14:15], v[26:27]
	v_pk_mul_f32 v[24:25], v[12:13], v[24:25]
	v_lshlrev_b32_e32 v12, 16, v136
	v_and_b32_e32 v13, 0xffff0000, v136
	v_lshlrev_b32_e32 v14, 16, v137
	v_and_b32_e32 v15, 0xffff0000, v137
	v_pk_mul_f32 v[14:15], v[18:19], v[14:15]
	v_pk_mul_f32 v[12:13], v[16:17], v[12:13]
	v_lshlrev_b32_e32 v16, 16, v138
	v_and_b32_e32 v17, 0xffff0000, v138
	v_lshlrev_b32_e32 v18, 16, v139
	v_and_b32_e32 v19, 0xffff0000, v139
	v_pk_mul_f32 v[10:11], v[10:11], v[18:19]
	v_pk_mul_f32 v[8:9], v[8:9], v[16:17]
	v_lshlrev_b32_e32 v16, 16, v84
	v_and_b32_e32 v17, 0xffff0000, v84
	v_lshlrev_b32_e32 v18, 16, v85
	v_and_b32_e32 v19, 0xffff0000, v85
	v_pk_mul_f32 v[6:7], v[6:7], v[18:19]
	v_pk_mul_f32 v[4:5], v[4:5], v[16:17]
	v_lshlrev_b32_e32 v16, 16, v86
	v_and_b32_e32 v17, 0xffff0000, v86
	v_lshlrev_b32_e32 v18, 16, v87
	v_and_b32_e32 v19, 0xffff0000, v87
	v_pk_mul_f32 v[2:3], v[2:3], v[18:19]
	v_pk_mul_f32 v[0:1], v[0:1], v[16:17]
	v_lshl_add_u64 v[16:17], s[2:3], 0, v[156:157]
	v_lshl_add_u64 v[18:19], s[2:3], 0, v[158:159]
	v_lshl_add_u64 v[16:17], v[16:17], 0, s[4:5]
	v_lshl_add_u64 v[18:19], v[18:19], 0, s[4:5]
	s_mov_b64 s[4:5], 0
.LBB0_818:
	s_add_u32 s16, s2, s4
	ds_read_b128 v[84:87], v164
	ds_read_b128 v[136:139], v164 offset:1024
	ds_read_b128 v[140:143], v164 offset:2048
	ds_read_b128 v[144:147], v164 offset:3072
	s_addc_u32 s17, s3, s5
	s_add_u32 s16, s16, 0xcd48500
	s_addc_u32 s17, s17, 0
	s_add_u32 s26, s38, s4
	s_addc_u32 s27, s39, s5
	s_cmpk_eq_i32 s4, 0x300
	s_cselect_b32 s37, s15, s17
	s_cselect_b32 s36, s1, s16
	s_cselect_b32 s17, s33, s27
	s_cselect_b32 s16, s25, s26
	s_mov_b32 m0, s60
	v_lshl_add_u64 v[160:161], v[16:17], 0, s[4:5]
	ds_read_b128 v[156:159], v165
	ds_read_b128 v[170:173], v165 offset:1024
	ds_read_b128 v[174:177], v165 offset:2048
	ds_read_b128 v[178:181], v165 offset:3072
	ds_read_b128 v[182:185], v165 offset:4096
	ds_read_b128 v[186:189], v165 offset:5120
	ds_read_b128 v[190:193], v165 offset:6144
	ds_read_b128 v[194:197], v165 offset:7168
	global_load_lds_dwordx4 v[160:161], off
	v_lshl_add_u64 v[160:161], v[18:19], 0, s[4:5]
	s_mov_b32 m0, s61
	s_nop 0
	global_load_lds_dwordx4 v[160:161], off
	s_waitcnt lgkmcnt(8)
	s_waitcnt vmcnt(10)
	s_barrier
	s_waitcnt lgkmcnt(0)
	s_setprio 1
	s_waitcnt lgkmcnt(0)
	v_mfma_f32_16x16x32_bf16 v[124:127], v[84:87], v[156:159], v[124:127]
	v_mfma_f32_16x16x32_bf16 v[120:123], v[140:143], v[156:159], v[120:123]
	v_mfma_f32_16x16x32_bf16 v[116:119], v[84:87], v[174:177], v[116:119]
	v_mfma_f32_16x16x32_bf16 v[112:115], v[140:143], v[174:177], v[112:115]
	v_mfma_f32_16x16x32_bf16 v[96:99], v[84:87], v[182:185], v[96:99]
	v_mfma_f32_16x16x32_bf16 v[100:103], v[140:143], v[182:185], v[100:103]
	v_mfma_f32_16x16x32_bf16 v[80:83], v[84:87], v[190:193], v[80:83]
	v_mfma_f32_16x16x32_bf16 v[76:79], v[140:143], v[190:193], v[76:79]
	v_mfma_f32_16x16x32_bf16 v[124:127], v[136:139], v[170:173], v[124:127]
	v_mfma_f32_16x16x32_bf16 v[120:123], v[144:147], v[170:173], v[120:123]
	v_mfma_f32_16x16x32_bf16 v[116:119], v[136:139], v[178:181], v[116:119]
	v_mfma_f32_16x16x32_bf16 v[112:115], v[144:147], v[178:181], v[112:115]
	v_mfma_f32_16x16x32_bf16 v[96:99], v[136:139], v[186:189], v[96:99]
	v_mfma_f32_16x16x32_bf16 v[100:103], v[144:147], v[186:189], v[100:103]
	v_mfma_f32_16x16x32_bf16 v[80:83], v[136:139], v[194:197], v[80:83]
	v_mfma_f32_16x16x32_bf16 v[76:79], v[144:147], v[194:197], v[76:79]
	s_setprio 0
	s_barrier
	s_mov_b32 m0, s62
	v_lshl_add_u64 v[160:161], s[16:17], 0, v[150:151]
	ds_read_b128 v[198:201], v166
	ds_read_b128 v[210:213], v166 offset:1024
	ds_read_b128 v[214:217], v166 offset:2048
	ds_read_b128 v[218:221], v166 offset:3072
	global_load_lds_dwordx4 v[160:161], off
	v_lshl_add_u64 v[222:223], s[16:17], 0, v[154:155]
	s_mov_b32 m0, s63
	s_nop 0
	global_load_lds_dwordx4 v[222:223], off
	s_waitcnt vmcnt(10)
	s_barrier
	s_waitcnt lgkmcnt(0)
	s_setprio 1
	s_waitcnt lgkmcnt(0)
	v_mfma_f32_16x16x32_bf16 v[128:131], v[198:201], v[156:159], v[128:131]
	v_mfma_f32_16x16x32_bf16 v[132:135], v[214:217], v[156:159], v[132:135]
	v_mfma_f32_16x16x32_bf16 v[104:107], v[198:201], v[174:177], v[104:107]
	v_mfma_f32_16x16x32_bf16 v[108:111], v[214:217], v[174:177], v[108:111]
	v_mfma_f32_16x16x32_bf16 v[88:91], v[198:201], v[182:185], v[88:91]
	v_mfma_f32_16x16x32_bf16 v[92:95], v[214:217], v[182:185], v[92:95]
	v_mfma_f32_16x16x32_bf16 v[68:71], v[198:201], v[190:193], v[68:71]
	v_mfma_f32_16x16x32_bf16 v[72:75], v[214:217], v[190:193], v[72:75]
	v_mfma_f32_16x16x32_bf16 v[128:131], v[210:213], v[170:173], v[128:131]
	v_mfma_f32_16x16x32_bf16 v[132:135], v[218:221], v[170:173], v[132:135]
	v_mfma_f32_16x16x32_bf16 v[104:107], v[210:213], v[178:181], v[104:107]
	v_mfma_f32_16x16x32_bf16 v[108:111], v[218:221], v[178:181], v[108:111]
	v_mfma_f32_16x16x32_bf16 v[88:91], v[210:213], v[186:189], v[88:91]
	v_mfma_f32_16x16x32_bf16 v[92:95], v[218:221], v[186:189], v[92:95]
	v_mfma_f32_16x16x32_bf16 v[68:71], v[210:213], v[194:197], v[68:71]
	v_mfma_f32_16x16x32_bf16 v[72:75], v[218:221], v[194:197], v[72:75]
	s_setprio 0
	s_mov_b32 m0, s19
	v_lshl_add_u64 v[224:225], s[36:37], 0, v[148:149]
	s_barrier
	ds_read_b128 v[156:159], v165 offset:16384
	ds_read_b128 v[170:173], v165 offset:17408
	ds_read_b128 v[174:177], v165 offset:18432
	ds_read_b128 v[178:181], v165 offset:19456
	ds_read_b128 v[182:185], v165 offset:20480
	ds_read_b128 v[186:189], v165 offset:21504
	ds_read_b128 v[190:193], v165 offset:22528
	ds_read_b128 v[194:197], v165 offset:23552
	global_load_lds_dwordx4 v[224:225], off
	v_lshl_add_u64 v[226:227], s[36:37], 0, v[152:153]
	s_mov_b32 m0, s20
	s_nop 0
	global_load_lds_dwordx4 v[226:227], off
	s_barrier
	s_waitcnt lgkmcnt(0)
	s_setprio 1
	s_waitcnt lgkmcnt(0)
	v_mfma_f32_16x16x32_bf16 v[60:63], v[84:87], v[156:159], v[60:63]
	v_mfma_f32_16x16x32_bf16 v[64:67], v[140:143], v[156:159], v[64:67]
	v_mfma_f32_16x16x32_bf16 v[44:47], v[84:87], v[174:177], v[44:47]
	v_mfma_f32_16x16x32_bf16 v[48:51], v[140:143], v[174:177], v[48:51]
	v_mfma_f32_16x16x32_bf16 v[28:31], v[84:87], v[182:185], v[28:31]
	v_mfma_f32_16x16x32_bf16 v[32:35], v[140:143], v[182:185], v[32:35]
	v_mfma_f32_16x16x32_bf16 v[12:15], v[84:87], v[190:193], v[12:15]
	v_mfma_f32_16x16x32_bf16 v[8:11], v[140:143], v[190:193], v[8:11]
	v_mfma_f32_16x16x32_bf16 v[60:63], v[136:139], v[170:173], v[60:63]
	v_mfma_f32_16x16x32_bf16 v[64:67], v[144:147], v[170:173], v[64:67]
	v_mfma_f32_16x16x32_bf16 v[44:47], v[136:139], v[178:181], v[44:47]
	v_mfma_f32_16x16x32_bf16 v[48:51], v[144:147], v[178:181], v[48:51]
	v_mfma_f32_16x16x32_bf16 v[28:31], v[136:139], v[186:189], v[28:31]
	v_mfma_f32_16x16x32_bf16 v[32:35], v[144:147], v[186:189], v[32:35]
	v_mfma_f32_16x16x32_bf16 v[12:15], v[136:139], v[194:197], v[12:15]
	v_mfma_f32_16x16x32_bf16 v[8:11], v[144:147], v[194:197], v[8:11]
	s_setprio 0
	s_barrier
	s_add_u32 s58, s16, 0x40000
	s_addc_u32 s59, s17, 0
	s_mov_b32 m0, s64
	v_lshl_add_u64 v[84:85], s[58:59], 0, v[150:151]
	global_load_lds_dwordx4 v[84:85], off
	v_lshl_add_u64 v[84:85], s[58:59], 0, v[154:155]
	s_mov_b32 m0, s65
	s_nop 0
	global_load_lds_dwordx4 v[84:85], off
	s_waitcnt vmcnt(10)
	s_barrier
	s_setprio 1
	v_mfma_f32_16x16x32_bf16 v[52:55], v[198:201], v[156:159], v[52:55]
	v_mfma_f32_16x16x32_bf16 v[56:59], v[214:217], v[156:159], v[56:59]
	v_mfma_f32_16x16x32_bf16 v[36:39], v[198:201], v[174:177], v[36:39]
	v_mfma_f32_16x16x32_bf16 v[40:43], v[214:217], v[174:177], v[40:43]
	v_mfma_f32_16x16x32_bf16 v[20:23], v[198:201], v[182:185], v[20:23]
	v_mfma_f32_16x16x32_bf16 v[24:27], v[214:217], v[182:185], v[24:27]
	v_mfma_f32_16x16x32_bf16 v[4:7], v[198:201], v[190:193], v[4:7]
	v_mfma_f32_16x16x32_bf16 v[0:3], v[214:217], v[190:193], v[0:3]
	v_mfma_f32_16x16x32_bf16 v[52:55], v[210:213], v[170:173], v[52:55]
	v_mfma_f32_16x16x32_bf16 v[56:59], v[218:221], v[170:173], v[56:59]
	v_mfma_f32_16x16x32_bf16 v[36:39], v[210:213], v[178:181], v[36:39]
	v_mfma_f32_16x16x32_bf16 v[40:43], v[218:221], v[178:181], v[40:43]
	v_mfma_f32_16x16x32_bf16 v[20:23], v[210:213], v[186:189], v[20:23]
	v_mfma_f32_16x16x32_bf16 v[24:27], v[218:221], v[186:189], v[24:27]
	v_mfma_f32_16x16x32_bf16 v[4:7], v[210:213], v[194:197], v[4:7]
	v_mfma_f32_16x16x32_bf16 v[0:3], v[218:221], v[194:197], v[0:3]
	s_setprio 0
	s_barrier
	ds_read_b128 v[84:87], v167
	ds_read_b128 v[136:139], v167 offset:1024
	ds_read_b128 v[140:143], v167 offset:2048
	ds_read_b128 v[144:147], v167 offset:3072
	s_add_u32 s36, s36, 0x40000
	s_addc_u32 s37, s37, 0
	s_mov_b32 m0, s21
	v_lshl_add_u64 v[198:199], s[36:37], 0, v[148:149]
	ds_read_b128 v[156:159], v165 offset:32768
	ds_read_b128 v[170:173], v165 offset:33792
	ds_read_b128 v[174:177], v165 offset:34816
	ds_read_b128 v[178:181], v165 offset:35840
	ds_read_b128 v[182:185], v165 offset:36864
	ds_read_b128 v[186:189], v165 offset:37888
	ds_read_b128 v[190:193], v165 offset:38912
	ds_read_b128 v[194:197], v165 offset:39936
	global_load_lds_dwordx4 v[198:199], off
	v_lshl_add_u64 v[198:199], s[36:37], 0, v[152:153]
	s_mov_b32 m0, s22
	s_nop 0
	global_load_lds_dwordx4 v[198:199], off
	s_waitcnt lgkmcnt(8)
	s_waitcnt vmcnt(10)
	s_barrier
	s_waitcnt lgkmcnt(0)
	s_setprio 1
	s_waitcnt lgkmcnt(0)
	v_mfma_f32_16x16x32_bf16 v[124:127], v[84:87], v[156:159], v[124:127]
	v_mfma_f32_16x16x32_bf16 v[120:123], v[140:143], v[156:159], v[120:123]
	v_mfma_f32_16x16x32_bf16 v[116:119], v[84:87], v[174:177], v[116:119]
	v_mfma_f32_16x16x32_bf16 v[112:115], v[140:143], v[174:177], v[112:115]
	v_mfma_f32_16x16x32_bf16 v[96:99], v[84:87], v[182:185], v[96:99]
	v_mfma_f32_16x16x32_bf16 v[100:103], v[140:143], v[182:185], v[100:103]
	v_mfma_f32_16x16x32_bf16 v[80:83], v[84:87], v[190:193], v[80:83]
	v_mfma_f32_16x16x32_bf16 v[76:79], v[140:143], v[190:193], v[76:79]
	v_mfma_f32_16x16x32_bf16 v[124:127], v[136:139], v[170:173], v[124:127]
	v_mfma_f32_16x16x32_bf16 v[120:123], v[144:147], v[170:173], v[120:123]
	v_mfma_f32_16x16x32_bf16 v[116:119], v[136:139], v[178:181], v[116:119]
	v_mfma_f32_16x16x32_bf16 v[112:115], v[144:147], v[178:181], v[112:115]
	v_mfma_f32_16x16x32_bf16 v[96:99], v[136:139], v[186:189], v[96:99]
	v_mfma_f32_16x16x32_bf16 v[100:103], v[144:147], v[186:189], v[100:103]
	v_mfma_f32_16x16x32_bf16 v[80:83], v[136:139], v[194:197], v[80:83]
	v_mfma_f32_16x16x32_bf16 v[76:79], v[144:147], v[194:197], v[76:79]
	s_setprio 0
	s_barrier
	s_mov_b32 m0, s66
	v_lshl_add_u64 v[160:161], v[160:161], 0, s[8:9]
	ds_read_b128 v[198:201], v168
	ds_read_b128 v[210:213], v168 offset:1024
	ds_read_b128 v[214:217], v168 offset:2048
	ds_read_b128 v[218:221], v168 offset:3072
	global_load_lds_dwordx4 v[160:161], off
	v_lshl_add_u64 v[160:161], v[222:223], 0, s[8:9]
	s_mov_b32 m0, s67
	s_nop 0
	global_load_lds_dwordx4 v[160:161], off
	s_waitcnt vmcnt(10)
	s_barrier
	s_waitcnt lgkmcnt(0)
	s_setprio 1
	s_waitcnt lgkmcnt(0)
	v_mfma_f32_16x16x32_bf16 v[128:131], v[198:201], v[156:159], v[128:131]
	v_mfma_f32_16x16x32_bf16 v[132:135], v[214:217], v[156:159], v[132:135]
	v_mfma_f32_16x16x32_bf16 v[104:107], v[198:201], v[174:177], v[104:107]
	v_mfma_f32_16x16x32_bf16 v[108:111], v[214:217], v[174:177], v[108:111]
	v_mfma_f32_16x16x32_bf16 v[88:91], v[198:201], v[182:185], v[88:91]
	v_mfma_f32_16x16x32_bf16 v[92:95], v[214:217], v[182:185], v[92:95]
	v_mfma_f32_16x16x32_bf16 v[68:71], v[198:201], v[190:193], v[68:71]
	v_mfma_f32_16x16x32_bf16 v[72:75], v[214:217], v[190:193], v[72:75]
	v_mfma_f32_16x16x32_bf16 v[128:131], v[210:213], v[170:173], v[128:131]
	v_mfma_f32_16x16x32_bf16 v[132:135], v[218:221], v[170:173], v[132:135]
	v_mfma_f32_16x16x32_bf16 v[104:107], v[210:213], v[178:181], v[104:107]
	v_mfma_f32_16x16x32_bf16 v[108:111], v[218:221], v[178:181], v[108:111]
	v_mfma_f32_16x16x32_bf16 v[88:91], v[210:213], v[186:189], v[88:91]
	v_mfma_f32_16x16x32_bf16 v[92:95], v[218:221], v[186:189], v[92:95]
	v_mfma_f32_16x16x32_bf16 v[68:71], v[210:213], v[194:197], v[68:71]
	v_mfma_f32_16x16x32_bf16 v[72:75], v[218:221], v[194:197], v[72:75]
	s_setprio 0
	s_mov_b32 m0, s23
	v_lshl_add_u64 v[160:161], v[224:225], 0, s[8:9]
	s_barrier
	ds_read_b128 v[156:159], v165 offset:49152
	ds_read_b128 v[170:173], v165 offset:50176
	ds_read_b128 v[174:177], v165 offset:51200
	ds_read_b128 v[178:181], v165 offset:52224
	ds_read_b128 v[182:185], v165 offset:53248
	ds_read_b128 v[186:189], v165 offset:54272
	ds_read_b128 v[190:193], v165 offset:55296
	ds_read_b128 v[194:197], v165 offset:56320
	global_load_lds_dwordx4 v[160:161], off
	v_lshl_add_u64 v[160:161], v[226:227], 0, s[8:9]
	s_mov_b32 m0, s24
	s_nop 0
	global_load_lds_dwordx4 v[160:161], off
	s_barrier
	s_waitcnt lgkmcnt(0)
	s_setprio 1
	s_waitcnt lgkmcnt(0)
	v_mfma_f32_16x16x32_bf16 v[60:63], v[84:87], v[156:159], v[60:63]
	v_mfma_f32_16x16x32_bf16 v[64:67], v[140:143], v[156:159], v[64:67]
	v_mfma_f32_16x16x32_bf16 v[44:47], v[84:87], v[174:177], v[44:47]
	v_mfma_f32_16x16x32_bf16 v[48:51], v[140:143], v[174:177], v[48:51]
	v_mfma_f32_16x16x32_bf16 v[28:31], v[84:87], v[182:185], v[28:31]
	v_mfma_f32_16x16x32_bf16 v[32:35], v[140:143], v[182:185], v[32:35]
	v_mfma_f32_16x16x32_bf16 v[12:15], v[84:87], v[190:193], v[12:15]
	v_mfma_f32_16x16x32_bf16 v[8:11], v[140:143], v[190:193], v[8:11]
	v_mfma_f32_16x16x32_bf16 v[60:63], v[136:139], v[170:173], v[60:63]
	v_mfma_f32_16x16x32_bf16 v[64:67], v[144:147], v[170:173], v[64:67]
	v_mfma_f32_16x16x32_bf16 v[44:47], v[136:139], v[178:181], v[44:47]
	v_mfma_f32_16x16x32_bf16 v[48:51], v[144:147], v[178:181], v[48:51]
	v_mfma_f32_16x16x32_bf16 v[28:31], v[136:139], v[186:189], v[28:31]
	v_mfma_f32_16x16x32_bf16 v[32:35], v[144:147], v[186:189], v[32:35]
	v_mfma_f32_16x16x32_bf16 v[12:15], v[136:139], v[194:197], v[12:15]
	v_mfma_f32_16x16x32_bf16 v[8:11], v[144:147], v[194:197], v[8:11]
	s_setprio 0
	s_barrier
	s_add_u32 s16, s16, 0x40080
	s_addc_u32 s17, s17, 0
	s_mov_b32 m0, s68
	v_lshl_add_u64 v[84:85], s[16:17], 0, v[150:151]
	global_load_lds_dwordx4 v[84:85], off
	v_lshl_add_u64 v[84:85], s[16:17], 0, v[154:155]
	s_mov_b32 m0, s69
	s_nop 0
	global_load_lds_dwordx4 v[84:85], off
	s_waitcnt vmcnt(10)
	s_barrier
	s_setprio 1
	v_mfma_f32_16x16x32_bf16 v[52:55], v[198:201], v[156:159], v[52:55]
	v_mfma_f32_16x16x32_bf16 v[56:59], v[214:217], v[156:159], v[56:59]
	v_mfma_f32_16x16x32_bf16 v[36:39], v[198:201], v[174:177], v[36:39]
	v_mfma_f32_16x16x32_bf16 v[40:43], v[214:217], v[174:177], v[40:43]
	v_mfma_f32_16x16x32_bf16 v[20:23], v[198:201], v[182:185], v[20:23]
	v_mfma_f32_16x16x32_bf16 v[24:27], v[214:217], v[182:185], v[24:27]
	v_mfma_f32_16x16x32_bf16 v[4:7], v[198:201], v[190:193], v[4:7]
	v_mfma_f32_16x16x32_bf16 v[0:3], v[214:217], v[190:193], v[0:3]
	v_mfma_f32_16x16x32_bf16 v[52:55], v[210:213], v[170:173], v[52:55]
	v_mfma_f32_16x16x32_bf16 v[56:59], v[218:221], v[170:173], v[56:59]
	v_mfma_f32_16x16x32_bf16 v[36:39], v[210:213], v[178:181], v[36:39]
	v_mfma_f32_16x16x32_bf16 v[40:43], v[218:221], v[178:181], v[40:43]
	v_mfma_f32_16x16x32_bf16 v[20:23], v[210:213], v[186:189], v[20:23]
	v_mfma_f32_16x16x32_bf16 v[24:27], v[218:221], v[186:189], v[24:27]
	v_mfma_f32_16x16x32_bf16 v[4:7], v[210:213], v[194:197], v[4:7]
	v_mfma_f32_16x16x32_bf16 v[0:3], v[218:221], v[194:197], v[0:3]
	s_setprio 0
	s_add_i32 s56, s56, 2
	s_add_u32 s4, s4, 0x100
	s_addc_u32 s5, s5, 0
	s_cmp_lt_u32 s56, 6
	s_barrier
	s_cbranch_scc1 .LBB0_818
	s_sext_i32_i8 s2, s0
	s_mul_i32 s0, s14, 0x240000
	s_lshl_b32 s1, s2, 17
	s_add_i32 s0, s0, s1
	s_add_i32 s0, s0, 0xa8000
	v_add_u32_e32 v16, s0, v169
	v_mov_b32_e32 v17, 0
	v_lshl_add_u64 v[86:87], s[70:71], 0, v[16:17]
	v_add_co_u32_e32 v18, vcc, 0x10000, v86
	v_lshl_add_u32 v136, s14, 8, v162
	s_nop 0
	v_addc_co_u32_e32 v19, vcc, 0, v87, vcc
	global_load_dwordx4 v[140:143], v[18:19], off
	v_add_co_u32_e32 v18, vcc, 0x1000, v86
	v_lshl_or_b32 v85, s2, 8, v163
	s_nop 0
	v_addc_co_u32_e32 v19, vcc, 0, v87, vcc
	global_load_dwordx4 v[144:147], v[18:19], off
	global_load_dwordx4 v[148:151], v16, s[70:71]
	v_add_co_u32_e32 v16, vcc, 0x11000, v86
	v_ashrrev_i32_e32 v137, 31, v136
	s_nop 0
	v_addc_co_u32_e32 v17, vcc, 0, v87, vcc
	v_add_co_u32_e32 v156, vcc, 0x2000, v86
	global_load_dwordx4 v[152:155], v[16:17], off
	s_mov_b64 s[0:1], vcc
	v_add_co_u32_e32 v160, vcc, 0x12000, v86
	s_mov_b64 s[8:9], vcc
	v_add_co_u32_e32 v164, vcc, 0x3000, v86
	v_or_b32_e32 v138, s18, v85
	s_mov_b64 s[4:5], vcc
	v_add_co_u32_e32 v16, vcc, 0x13000, v86
	v_or_b32_e32 v84, 16, v136
	v_lshlrev_b64 v[158:159], 11, v[136:137]
	v_ashrrev_i32_e32 v139, 31, v138
	v_addc_co_u32_e32 v17, vcc, 0, v87, vcc
	v_ashrrev_i32_e32 v85, 31, v84
	v_lshl_add_u64 v[158:159], s[10:11], 0, v[158:159]
	v_lshlrev_b64 v[138:139], 1, v[138:139]
	v_addc_co_u32_e64 v157, vcc, 0, v87, s[0:1]
	global_load_dwordx4 v[16:19], v[16:17], off
	v_lshlrev_b64 v[168:169], 11, v[84:85]
	v_lshl_add_u64 v[84:85], v[158:159], 0, v[138:139]
	global_load_dwordx4 v[156:159], v[156:157], off
	v_addc_co_u32_e64 v161, vcc, 0, v87, s[8:9]
	v_addc_co_u32_e64 v165, vcc, 0, v87, s[4:5]
	global_load_dwordx4 v[160:163], v[160:161], off
	s_nop 0
	global_load_dwordx4 v[164:167], v[164:165], off
	s_mov_b32 s0, 0x120000
	v_readlane_b32 s80, v234, 43
	s_cmpk_gt_u32 s13, 0xff
	v_readlane_b32 s81, v234, 44
	s_waitcnt vmcnt(0)
	v_lshlrev_b32_e32 v172, 16, v140
	v_and_b32_e32 v173, 0xffff0000, v140
	v_lshlrev_b32_e32 v140, 16, v141
	v_and_b32_e32 v141, 0xffff0000, v141
	v_lshlrev_b32_e32 v170, 16, v142
	v_and_b32_e32 v171, 0xffff0000, v142
	v_lshlrev_b32_e32 v142, 16, v143
	v_and_b32_e32 v143, 0xffff0000, v143
	v_pk_mul_f32 v[130:131], v[130:131], v[140:141]
	v_pk_mul_f32 v[128:129], v[128:129], v[172:173]
	v_pk_mul_f32 v[134:135], v[134:135], v[142:143]
	v_pk_mul_f32 v[132:133], v[132:133], v[170:171]
	v_cvt_pk_bf16_f32 v128, v128, v129
	v_cvt_pk_bf16_f32 v129, v130, v131
	v_cvt_pk_bf16_f32 v131, v134, v135
	v_lshlrev_b32_e32 v134, 16, v149
	v_cvt_pk_bf16_f32 v130, v132, v133
	global_store_dwordx4 v[84:85], v[128:131], off offset:256
	v_lshlrev_b32_e32 v132, 16, v148
	v_and_b32_e32 v133, 0xffff0000, v148
	v_lshlrev_b32_e32 v128, 16, v150
	v_and_b32_e32 v129, 0xffff0000, v150
	v_lshlrev_b32_e32 v130, 16, v151
	v_and_b32_e32 v131, 0xffff0000, v151
	v_and_b32_e32 v135, 0xffff0000, v149
	v_pk_mul_f32 v[130:131], v[122:123], v[130:131]
	v_pk_mul_f32 v[122:123], v[120:121], v[128:129]
	v_pk_mul_f32 v[120:121], v[124:125], v[132:133]
	v_pk_mul_f32 v[126:127], v[126:127], v[134:135]
	v_cvt_pk_bf16_f32 v120, v120, v121
	v_lshlrev_b32_e32 v140, 16, v146
	v_cvt_pk_bf16_f32 v121, v126, v127
	v_cvt_pk_bf16_f32 v122, v122, v123
	v_cvt_pk_bf16_f32 v123, v130, v131
	global_store_dwordx4 v[84:85], v[120:123], off
	v_and_b32_e32 v141, 0xffff0000, v146
	s_nop 0
	v_lshlrev_b32_e32 v120, 16, v147
	v_and_b32_e32 v121, 0xffff0000, v147
	v_pk_mul_f32 v[120:121], v[114:115], v[120:121]
	v_pk_mul_f32 v[114:115], v[112:113], v[140:141]
	v_lshlrev_b32_e32 v112, 16, v144
	v_and_b32_e32 v113, 0xffff0000, v144
	v_lshlrev_b32_e32 v122, 16, v145
	v_and_b32_e32 v123, 0xffff0000, v145
	v_pk_mul_f32 v[112:113], v[116:117], v[112:113]
	v_lshl_add_u64 v[116:117], s[10:11], 0, v[168:169]
	v_pk_mul_f32 v[118:119], v[118:119], v[122:123]
	v_cvt_pk_bf16_f32 v112, v112, v113
	v_cvt_pk_bf16_f32 v114, v114, v115
	v_cvt_pk_bf16_f32 v115, v120, v121
	v_lshl_add_u64 v[116:117], v[116:117], 0, v[138:139]
	v_cvt_pk_bf16_f32 v113, v118, v119
	global_store_dwordx4 v[116:117], v[112:115], off
	s_nop 1
	v_lshlrev_b32_e32 v112, 16, v154
	v_and_b32_e32 v113, 0xffff0000, v154
	v_lshlrev_b32_e32 v114, 16, v155
	v_and_b32_e32 v115, 0xffff0000, v155
	v_pk_mul_f32 v[110:111], v[110:111], v[114:115]
	v_pk_mul_f32 v[108:109], v[108:109], v[112:113]
	v_lshlrev_b32_e32 v112, 16, v152
	v_and_b32_e32 v113, 0xffff0000, v152
	v_lshlrev_b32_e32 v114, 16, v153
	v_and_b32_e32 v115, 0xffff0000, v153
	v_pk_mul_f32 v[106:107], v[106:107], v[114:115]
	v_pk_mul_f32 v[104:105], v[104:105], v[112:113]
	s_nop 0
	v_cvt_pk_bf16_f32 v104, v104, v105
	v_cvt_pk_bf16_f32 v105, v106, v107
	v_cvt_pk_bf16_f32 v106, v108, v109
	v_cvt_pk_bf16_f32 v107, v110, v111
	global_store_dwordx4 v[116:117], v[104:107], off offset:256
	v_lshlrev_b32_e32 v108, 16, v159
	v_and_b32_e32 v109, 0xffff0000, v159
	v_or_b32_e32 v104, 32, v136
	v_lshlrev_b32_e32 v106, 16, v158
	v_and_b32_e32 v107, 0xffff0000, v158
	v_ashrrev_i32_e32 v105, 31, v104
	v_pk_mul_f32 v[102:103], v[102:103], v[108:109]
	v_pk_mul_f32 v[100:101], v[100:101], v[106:107]
	v_lshlrev_b32_e32 v106, 16, v156
	v_and_b32_e32 v107, 0xffff0000, v156
	v_lshlrev_b32_e32 v108, 16, v157
	v_and_b32_e32 v109, 0xffff0000, v157
	v_lshlrev_b64 v[104:105], 11, v[104:105]
	v_pk_mul_f32 v[98:99], v[98:99], v[108:109]
	v_pk_mul_f32 v[96:97], v[96:97], v[106:107]
	s_nop 0
	v_cvt_pk_bf16_f32 v96, v96, v97
	v_cvt_pk_bf16_f32 v97, v98, v99
	v_cvt_pk_bf16_f32 v98, v100, v101
	v_lshl_add_u64 v[100:101], s[10:11], 0, v[104:105]
	v_lshl_add_u64 v[100:101], v[100:101], 0, v[138:139]
	v_cvt_pk_bf16_f32 v99, v102, v103
	global_store_dwordx4 v[100:101], v[96:99], off
	s_nop 1
	v_lshlrev_b32_e32 v96, 16, v162
	v_and_b32_e32 v97, 0xffff0000, v162
	v_lshlrev_b32_e32 v98, 16, v163
	v_and_b32_e32 v99, 0xffff0000, v163
	v_pk_mul_f32 v[92:93], v[92:93], v[96:97]
	v_lshlrev_b32_e32 v96, 16, v160
	v_and_b32_e32 v97, 0xffff0000, v160
	v_pk_mul_f32 v[94:95], v[94:95], v[98:99]
	v_lshlrev_b32_e32 v98, 16, v161
	v_and_b32_e32 v99, 0xffff0000, v161
	v_pk_mul_f32 v[88:89], v[88:89], v[96:97]
	v_pk_mul_f32 v[90:91], v[90:91], v[98:99]
	v_cvt_pk_bf16_f32 v88, v88, v89
	s_nop 0
	v_cvt_pk_bf16_f32 v89, v90, v91
	v_cvt_pk_bf16_f32 v90, v92, v93
	v_cvt_pk_bf16_f32 v91, v94, v95
	global_store_dwordx4 v[100:101], v[88:91], off offset:256
	v_lshlrev_b32_e32 v92, 16, v167
	v_and_b32_e32 v93, 0xffff0000, v167
	v_or_b32_e32 v88, 48, v136
	v_ashrrev_i32_e32 v89, 31, v88
	v_lshlrev_b32_e32 v90, 16, v166
	v_and_b32_e32 v91, 0xffff0000, v166
	v_lshlrev_b64 v[88:89], 11, v[88:89]
	v_pk_mul_f32 v[92:93], v[78:79], v[92:93]
	v_pk_mul_f32 v[78:79], v[76:77], v[90:91]
	v_lshlrev_b32_e32 v76, 16, v164
	v_and_b32_e32 v77, 0xffff0000, v164
	v_lshlrev_b32_e32 v90, 16, v165
	v_and_b32_e32 v91, 0xffff0000, v165
	v_pk_mul_f32 v[76:77], v[80:81], v[76:77]
	v_lshl_add_u64 v[80:81], s[10:11], 0, v[88:89]
	v_pk_mul_f32 v[82:83], v[82:83], v[90:91]
	v_cvt_pk_bf16_f32 v76, v76, v77
	v_lshl_add_u64 v[80:81], v[80:81], 0, v[138:139]
	v_cvt_pk_bf16_f32 v77, v82, v83
	v_cvt_pk_bf16_f32 v78, v78, v79
	v_cvt_pk_bf16_f32 v79, v92, v93
	global_store_dwordx4 v[80:81], v[76:79], off
	s_nop 1
	v_lshlrev_b32_e32 v76, 16, v18
	v_and_b32_e32 v77, 0xffff0000, v18
	v_lshlrev_b32_e32 v18, 16, v19
	v_and_b32_e32 v19, 0xffff0000, v19
	v_pk_mul_f32 v[74:75], v[74:75], v[18:19]
	v_pk_mul_f32 v[18:19], v[72:73], v[76:77]
	v_lshlrev_b32_e32 v72, 16, v16
	v_and_b32_e32 v73, 0xffff0000, v16
	v_lshlrev_b32_e32 v16, 16, v17
	v_and_b32_e32 v17, 0xffff0000, v17
	v_pk_mul_f32 v[70:71], v[70:71], v[16:17]
	v_pk_mul_f32 v[16:17], v[68:69], v[72:73]
	v_cvt_pk_bf16_f32 v18, v18, v19
	v_cvt_pk_bf16_f32 v19, v74, v75
	s_nop 0
	v_cvt_pk_bf16_f32 v16, v16, v17
	v_cvt_pk_bf16_f32 v17, v70, v71
	global_store_dwordx4 v[80:81], v[16:19], off offset:256
	s_nop 1
	v_add_co_u32_e32 v16, vcc, s0, v86
	s_mov_b32 s0, 0x131000
	s_nop 0
	v_addc_co_u32_e32 v17, vcc, 0, v87, vcc
	global_load_dwordx4 v[72:75], v[16:17], off
	v_add_co_u32_e32 v16, vcc, s0, v86
	s_mov_b32 s0, 0x122000
	s_nop 0
	v_addc_co_u32_e32 v17, vcc, 0, v87, vcc
	global_load_dwordx4 v[76:79], v[16:17], off offset:-4096
	v_add_co_u32_e32 v18, vcc, s0, v86
	s_mov_b32 s0, 0x123000
	s_nop 0
	v_addc_co_u32_e32 v19, vcc, 0, v87, vcc
	global_load_dwordx4 v[80:83], v[18:19], off offset:-4096
	global_load_dwordx4 v[88:91], v[16:17], off
	v_add_co_u32_e32 v16, vcc, s0, v86
	s_mov_b32 s0, 0x133000
	s_nop 0
	v_addc_co_u32_e32 v17, vcc, 0, v87, vcc
	global_load_dwordx4 v[68:71], v[16:17], off
	global_load_dwordx4 v[92:95], v[18:19], off
	v_add_co_u32_e32 v16, vcc, s0, v86
	s_mov_b64 s[0:1], 0x40000
	s_nop 0
	v_addc_co_u32_e32 v17, vcc, 0, v87, vcc
	global_load_dwordx4 v[96:99], v[16:17], off offset:-4096
	s_nop 0
	global_load_dwordx4 v[16:19], v[16:17], off
	s_waitcnt vmcnt(0)
	v_lshlrev_b32_e32 v86, 16, v74
	v_and_b32_e32 v87, 0xffff0000, v74
	v_lshlrev_b32_e32 v74, 16, v75
	v_and_b32_e32 v75, 0xffff0000, v75
	v_pk_mul_f32 v[66:67], v[66:67], v[74:75]
	v_lshlrev_b32_e32 v74, 16, v72
	v_and_b32_e32 v75, 0xffff0000, v72
	v_lshlrev_b32_e32 v72, 16, v73
	v_and_b32_e32 v73, 0xffff0000, v73
	v_pk_mul_f32 v[64:65], v[64:65], v[86:87]
	v_pk_mul_f32 v[62:63], v[62:63], v[72:73]
	v_pk_mul_f32 v[60:61], v[60:61], v[74:75]
	s_nop 0
	v_cvt_pk_bf16_f32 v60, v60, v61
	v_cvt_pk_bf16_f32 v61, v62, v63
	v_cvt_pk_bf16_f32 v62, v64, v65
	v_lshl_add_u64 v[64:65], v[84:85], 0, s[0:1]
	s_mov_b32 s0, 0x40000
	v_cvt_pk_bf16_f32 v63, v66, v67
	v_add_co_u32_e32 v66, vcc, s0, v84
	s_mov_b64 s[0:1], 0x48000
	s_nop 0
	v_addc_co_u32_e32 v67, vcc, 0, v85, vcc
	global_store_dwordx4 v[66:67], v[60:63], off
	s_nop 1
	v_lshlrev_b32_e32 v60, 16, v78
	v_and_b32_e32 v61, 0xffff0000, v78
	v_lshlrev_b32_e32 v62, 16, v79
	v_and_b32_e32 v63, 0xffff0000, v79
	v_pk_mul_f32 v[58:59], v[58:59], v[62:63]
	v_pk_mul_f32 v[56:57], v[56:57], v[60:61]
	v_lshlrev_b32_e32 v60, 16, v76
	v_and_b32_e32 v61, 0xffff0000, v76
	v_lshlrev_b32_e32 v62, 16, v77
	v_and_b32_e32 v63, 0xffff0000, v77
	v_pk_mul_f32 v[54:55], v[54:55], v[62:63]
	v_pk_mul_f32 v[52:53], v[52:53], v[60:61]
	s_nop 0
	v_cvt_pk_bf16_f32 v52, v52, v53
	v_cvt_pk_bf16_f32 v53, v54, v55
	v_cvt_pk_bf16_f32 v54, v56, v57
	v_cvt_pk_bf16_f32 v55, v58, v59
	global_store_dwordx4 v[64:65], v[52:55], off offset:256
	s_nop 1
	v_lshlrev_b32_e32 v52, 16, v82
	v_and_b32_e32 v53, 0xffff0000, v82
	v_lshlrev_b32_e32 v54, 16, v83
	v_and_b32_e32 v55, 0xffff0000, v83
	v_pk_mul_f32 v[50:51], v[50:51], v[54:55]
	v_pk_mul_f32 v[48:49], v[48:49], v[52:53]
	v_lshlrev_b32_e32 v52, 16, v80
	v_and_b32_e32 v53, 0xffff0000, v80
	v_lshlrev_b32_e32 v54, 16, v81
	v_and_b32_e32 v55, 0xffff0000, v81
	v_pk_mul_f32 v[46:47], v[46:47], v[54:55]
	v_pk_mul_f32 v[44:45], v[44:45], v[52:53]
	s_nop 0
	v_cvt_pk_bf16_f32 v44, v44, v45
	v_cvt_pk_bf16_f32 v45, v46, v47
	v_cvt_pk_bf16_f32 v46, v48, v49
	v_lshl_add_u64 v[48:49], v[84:85], 0, s[0:1]
	s_mov_b32 s0, 0x48000
	v_cvt_pk_bf16_f32 v47, v50, v51
	v_add_co_u32_e32 v50, vcc, s0, v84
	s_mov_b64 s[0:1], 0x50000
	s_nop 0
	v_addc_co_u32_e32 v51, vcc, 0, v85, vcc
	global_store_dwordx4 v[50:51], v[44:47], off
	s_nop 1
	v_lshlrev_b32_e32 v44, 16, v90
	v_and_b32_e32 v45, 0xffff0000, v90
	v_lshlrev_b32_e32 v46, 16, v91
	v_and_b32_e32 v47, 0xffff0000, v91
	v_pk_mul_f32 v[42:43], v[42:43], v[46:47]
	v_pk_mul_f32 v[40:41], v[40:41], v[44:45]
	v_lshlrev_b32_e32 v44, 16, v88
	v_and_b32_e32 v45, 0xffff0000, v88
	v_lshlrev_b32_e32 v46, 16, v89
	v_and_b32_e32 v47, 0xffff0000, v89
	v_pk_mul_f32 v[38:39], v[38:39], v[46:47]
	v_pk_mul_f32 v[36:37], v[36:37], v[44:45]
	s_nop 0
	v_cvt_pk_bf16_f32 v36, v36, v37
	v_cvt_pk_bf16_f32 v37, v38, v39
	v_cvt_pk_bf16_f32 v38, v40, v41
	v_cvt_pk_bf16_f32 v39, v42, v43
	global_store_dwordx4 v[48:49], v[36:39], off offset:256
	s_nop 1
	v_lshlrev_b32_e32 v36, 16, v94
	v_and_b32_e32 v37, 0xffff0000, v94
	v_lshlrev_b32_e32 v38, 16, v95
	v_and_b32_e32 v39, 0xffff0000, v95
	v_pk_mul_f32 v[34:35], v[34:35], v[38:39]
	v_pk_mul_f32 v[32:33], v[32:33], v[36:37]
	v_lshlrev_b32_e32 v36, 16, v92
	v_and_b32_e32 v37, 0xffff0000, v92
	v_lshlrev_b32_e32 v38, 16, v93
	v_and_b32_e32 v39, 0xffff0000, v93
	v_pk_mul_f32 v[30:31], v[30:31], v[38:39]
	v_pk_mul_f32 v[28:29], v[28:29], v[36:37]
	s_nop 0
	v_cvt_pk_bf16_f32 v28, v28, v29
	v_cvt_pk_bf16_f32 v29, v30, v31
	v_cvt_pk_bf16_f32 v30, v32, v33
	v_lshl_add_u64 v[32:33], v[84:85], 0, s[0:1]
	s_mov_b32 s0, 0x50000
	v_cvt_pk_bf16_f32 v31, v34, v35
	v_add_co_u32_e32 v34, vcc, s0, v84
	s_mov_b64 s[0:1], 0x58000
	s_nop 0
	v_addc_co_u32_e32 v35, vcc, 0, v85, vcc
	global_store_dwordx4 v[34:35], v[28:31], off
	s_nop 1
	v_lshlrev_b32_e32 v28, 16, v98
	v_and_b32_e32 v29, 0xffff0000, v98
	v_lshlrev_b32_e32 v30, 16, v99
	v_and_b32_e32 v31, 0xffff0000, v99
	v_pk_mul_f32 v[26:27], v[26:27], v[30:31]
	v_pk_mul_f32 v[24:25], v[24:25], v[28:29]
	v_lshlrev_b32_e32 v28, 16, v96
	v_and_b32_e32 v29, 0xffff0000, v96
	v_lshlrev_b32_e32 v30, 16, v97
	v_and_b32_e32 v31, 0xffff0000, v97
	v_pk_mul_f32 v[22:23], v[22:23], v[30:31]
	v_pk_mul_f32 v[20:21], v[20:21], v[28:29]
	s_nop 0
	v_cvt_pk_bf16_f32 v20, v20, v21
	v_cvt_pk_bf16_f32 v21, v22, v23
	v_cvt_pk_bf16_f32 v22, v24, v25
	v_cvt_pk_bf16_f32 v23, v26, v27
	global_store_dwordx4 v[32:33], v[20:23], off offset:256
	s_nop 1
	v_lshlrev_b32_e32 v20, 16, v70
	v_and_b32_e32 v21, 0xffff0000, v70
	v_lshlrev_b32_e32 v22, 16, v71
	v_and_b32_e32 v23, 0xffff0000, v71
	v_pk_mul_f32 v[22:23], v[10:11], v[22:23]
	v_pk_mul_f32 v[10:11], v[8:9], v[20:21]
	v_lshlrev_b32_e32 v8, 16, v68
	v_and_b32_e32 v9, 0xffff0000, v68
	v_lshlrev_b32_e32 v20, 16, v69
	v_and_b32_e32 v21, 0xffff0000, v69
	v_pk_mul_f32 v[14:15], v[14:15], v[20:21]
	v_pk_mul_f32 v[8:9], v[12:13], v[8:9]
	v_lshl_add_u64 v[12:13], v[84:85], 0, s[0:1]
	s_mov_b32 s0, 0x58000
	v_cvt_pk_bf16_f32 v8, v8, v9
	v_cvt_pk_bf16_f32 v9, v14, v15
	v_add_co_u32_e32 v14, vcc, s0, v84
	v_cvt_pk_bf16_f32 v10, v10, v11
	v_cvt_pk_bf16_f32 v11, v22, v23
	s_nop 1
	v_addc_co_u32_e32 v15, vcc, 0, v85, vcc
	global_store_dwordx4 v[14:15], v[8:11], off
	s_nop 1
	v_lshlrev_b32_e32 v8, 16, v18
	v_and_b32_e32 v9, 0xffff0000, v18
	v_lshlrev_b32_e32 v10, 16, v19
	v_and_b32_e32 v11, 0xffff0000, v19
	v_pk_mul_f32 v[10:11], v[2:3], v[10:11]
	v_pk_mul_f32 v[2:3], v[0:1], v[8:9]
	v_lshlrev_b32_e32 v0, 16, v16
	v_and_b32_e32 v1, 0xffff0000, v16
	v_lshlrev_b32_e32 v8, 16, v17
	v_and_b32_e32 v9, 0xffff0000, v17
	v_pk_mul_f32 v[0:1], v[4:5], v[0:1]
	v_pk_mul_f32 v[6:7], v[6:7], v[8:9]
	v_cvt_pk_bf16_f32 v0, v0, v1
	v_cvt_pk_bf16_f32 v2, v2, v3
	v_cvt_pk_bf16_f32 v3, v10, v11
	s_nop 0
	v_cvt_pk_bf16_f32 v1, v6, v7
	global_store_dwordx4 v[12:13], v[0:3], off offset:256
	s_waitcnt vmcnt(0)
	s_cbranch_scc1 .LBB0_821
	s_barrier

.LBB0_898:
	v_add_u32_e32 v158, s64, v144
	s_add_u32 s26, s6, s56
	ds_read_b128 v[146:149], v158
	ds_read_b128 v[150:153], v158 offset:1024
	ds_read_b128 v[154:157], v158 offset:2048
	ds_read_b128 v[158:161], v158 offset:3072
	s_addc_u32 s27, s7, s57
	s_add_u32 s26, s26, 0x100
	s_addc_u32 s27, s27, 0
	s_add_u32 s58, s67, s56
	s_addc_u32 s59, s68, s57
	s_cmpk_eq_i32 s56, 0x700
	s_cselect_b32 s61, s17, s27
	s_cselect_b32 s60, s69, s26
	s_cselect_b32 s59, s15, s59
	s_cselect_b32 s58, s70, s58
	v_lshl_add_u64 v[194:195], v[140:141], 0, s[56:57]
	s_add_i32 m0, s3, 0xc000
	ds_read_b128 v[162:165], v145
	ds_read_b128 v[166:169], v145 offset:1024
	ds_read_b128 v[170:173], v145 offset:2048
	ds_read_b128 v[174:177], v145 offset:3072
	ds_read_b128 v[178:181], v145 offset:4096
	ds_read_b128 v[182:185], v145 offset:5120
	ds_read_b128 v[186:189], v145 offset:6144
	ds_read_b128 v[190:193], v145 offset:7168
	global_load_lds_dwordx4 v[194:195], off
	v_lshl_add_u64 v[194:195], v[142:143], 0, s[56:57]
	s_add_i32 m0, s3, 0xe000
	s_nop 0
	global_load_lds_dwordx4 v[194:195], off
	s_waitcnt lgkmcnt(8)
	s_waitcnt vmcnt(10)
	s_barrier
	s_waitcnt lgkmcnt(0)
	s_setprio 1
	s_waitcnt lgkmcnt(0)
	v_mfma_f32_16x16x32_bf16 v[124:127], v[146:149], v[162:165], v[124:127]
	v_mfma_f32_16x16x32_bf16 v[120:123], v[154:157], v[162:165], v[120:123]
	v_mfma_f32_16x16x32_bf16 v[108:111], v[146:149], v[170:173], v[108:111]
	v_mfma_f32_16x16x32_bf16 v[104:107], v[154:157], v[170:173], v[104:107]
	v_mfma_f32_16x16x32_bf16 v[92:95], v[146:149], v[178:181], v[92:95]
	v_mfma_f32_16x16x32_bf16 v[88:91], v[154:157], v[178:181], v[88:91]
	v_mfma_f32_16x16x32_bf16 v[76:79], v[146:149], v[186:189], v[76:79]
	v_mfma_f32_16x16x32_bf16 v[72:75], v[154:157], v[186:189], v[72:75]
	v_mfma_f32_16x16x32_bf16 v[124:127], v[150:153], v[166:169], v[124:127]
	v_mfma_f32_16x16x32_bf16 v[120:123], v[158:161], v[166:169], v[120:123]
	v_mfma_f32_16x16x32_bf16 v[108:111], v[150:153], v[174:177], v[108:111]
	v_mfma_f32_16x16x32_bf16 v[104:107], v[158:161], v[174:177], v[104:107]
	v_mfma_f32_16x16x32_bf16 v[92:95], v[150:153], v[182:185], v[92:95]
	v_mfma_f32_16x16x32_bf16 v[88:91], v[158:161], v[182:185], v[88:91]
	v_mfma_f32_16x16x32_bf16 v[76:79], v[150:153], v[190:193], v[76:79]
	v_mfma_f32_16x16x32_bf16 v[72:75], v[158:161], v[190:193], v[72:75]
	s_setprio 0
	s_barrier
	s_add_i32 s26, s64, s22
	v_add_u32_e32 v209, s65, v144
	v_lshl_add_u64 v[218:219], s[58:59], 0, v[128:129]
	s_mov_b32 m0, s26
	ds_read_b128 v[194:197], v209
	ds_read_b128 v[198:201], v209 offset:1024
	ds_read_b128 v[210:213], v209 offset:2048
	ds_read_b128 v[214:217], v209 offset:3072
	global_load_lds_dwordx4 v[218:219], off
	v_lshl_add_u64 v[220:221], s[58:59], 0, v[130:131]
	s_add_i32 m0, s26, 0x2000
	s_nop 0
	global_load_lds_dwordx4 v[220:221], off
	s_waitcnt vmcnt(10)
	s_barrier
	s_waitcnt lgkmcnt(0)
	s_setprio 1
	s_waitcnt lgkmcnt(0)
	v_mfma_f32_16x16x32_bf16 v[116:119], v[194:197], v[162:165], v[116:119]
	v_mfma_f32_16x16x32_bf16 v[112:115], v[210:213], v[162:165], v[112:115]
	v_mfma_f32_16x16x32_bf16 v[100:103], v[194:197], v[170:173], v[100:103]
	v_mfma_f32_16x16x32_bf16 v[96:99], v[210:213], v[170:173], v[96:99]
	v_mfma_f32_16x16x32_bf16 v[84:87], v[194:197], v[178:181], v[84:87]
	v_mfma_f32_16x16x32_bf16 v[80:83], v[210:213], v[178:181], v[80:83]
	v_mfma_f32_16x16x32_bf16 v[68:71], v[194:197], v[186:189], v[68:71]
	v_mfma_f32_16x16x32_bf16 v[64:67], v[210:213], v[186:189], v[64:67]
	v_mfma_f32_16x16x32_bf16 v[116:119], v[198:201], v[166:169], v[116:119]
	v_mfma_f32_16x16x32_bf16 v[112:115], v[214:217], v[166:169], v[112:115]
	v_mfma_f32_16x16x32_bf16 v[100:103], v[198:201], v[174:177], v[100:103]
	v_mfma_f32_16x16x32_bf16 v[96:99], v[214:217], v[174:177], v[96:99]
	v_mfma_f32_16x16x32_bf16 v[84:87], v[198:201], v[182:185], v[84:87]
	v_mfma_f32_16x16x32_bf16 v[80:83], v[214:217], v[182:185], v[80:83]
	v_mfma_f32_16x16x32_bf16 v[68:71], v[198:201], v[190:193], v[68:71]
	v_mfma_f32_16x16x32_bf16 v[64:67], v[214:217], v[190:193], v[64:67]
	s_setprio 0
	s_mov_b32 m0, s3
	v_lshl_add_u64 v[222:223], s[60:61], 0, v[128:129]
	s_barrier
	ds_read_b128 v[162:165], v145 offset:16384
	ds_read_b128 v[166:169], v145 offset:17408
	ds_read_b128 v[170:173], v145 offset:18432
	ds_read_b128 v[174:177], v145 offset:19456
	ds_read_b128 v[178:181], v145 offset:20480
	ds_read_b128 v[182:185], v145 offset:21504
	ds_read_b128 v[186:189], v145 offset:22528
	ds_read_b128 v[190:193], v145 offset:23552
	global_load_lds_dwordx4 v[222:223], off
	v_lshl_add_u64 v[224:225], s[60:61], 0, v[130:131]
	s_mov_b32 m0, s23
	s_nop 0
	global_load_lds_dwordx4 v[224:225], off
	s_barrier
	s_waitcnt lgkmcnt(0)
	s_setprio 1
	s_waitcnt lgkmcnt(0)
	v_mfma_f32_16x16x32_bf16 v[60:63], v[146:149], v[162:165], v[60:63]
	v_mfma_f32_16x16x32_bf16 v[56:59], v[154:157], v[162:165], v[56:59]
	v_mfma_f32_16x16x32_bf16 v[44:47], v[146:149], v[170:173], v[44:47]
	v_mfma_f32_16x16x32_bf16 v[40:43], v[154:157], v[170:173], v[40:43]
	v_mfma_f32_16x16x32_bf16 v[28:31], v[146:149], v[178:181], v[28:31]
	v_mfma_f32_16x16x32_bf16 v[24:27], v[154:157], v[178:181], v[24:27]
	v_mfma_f32_16x16x32_bf16 v[12:15], v[146:149], v[186:189], v[12:15]
	v_mfma_f32_16x16x32_bf16 v[8:11], v[154:157], v[186:189], v[8:11]
	v_mfma_f32_16x16x32_bf16 v[60:63], v[150:153], v[166:169], v[60:63]
	v_mfma_f32_16x16x32_bf16 v[56:59], v[158:161], v[166:169], v[56:59]
	v_mfma_f32_16x16x32_bf16 v[44:47], v[150:153], v[174:177], v[44:47]
	v_mfma_f32_16x16x32_bf16 v[40:43], v[158:161], v[174:177], v[40:43]
	v_mfma_f32_16x16x32_bf16 v[28:31], v[150:153], v[182:185], v[28:31]
	v_mfma_f32_16x16x32_bf16 v[24:27], v[158:161], v[182:185], v[24:27]
	v_mfma_f32_16x16x32_bf16 v[12:15], v[150:153], v[190:193], v[12:15]
	v_mfma_f32_16x16x32_bf16 v[8:11], v[158:161], v[190:193], v[8:11]
	s_setprio 0
	s_barrier
	s_add_u32 s72, s58, 0x40000
	s_addc_u32 s73, s59, 0
	s_add_i32 s26, s65, s22
	v_lshl_add_u64 v[146:147], s[72:73], 0, v[128:129]
	s_mov_b32 m0, s26
	s_nop 0
	global_load_lds_dwordx4 v[146:147], off
	v_lshl_add_u64 v[146:147], s[72:73], 0, v[130:131]
	s_add_i32 m0, s26, 0x2000
	s_nop 0
	global_load_lds_dwordx4 v[146:147], off
	s_waitcnt vmcnt(10)
	s_barrier
	s_setprio 1
	v_mfma_f32_16x16x32_bf16 v[52:55], v[194:197], v[162:165], v[52:55]
	v_mfma_f32_16x16x32_bf16 v[48:51], v[210:213], v[162:165], v[48:51]
	v_mfma_f32_16x16x32_bf16 v[36:39], v[194:197], v[170:173], v[36:39]
	v_mfma_f32_16x16x32_bf16 v[32:35], v[210:213], v[170:173], v[32:35]
	v_mfma_f32_16x16x32_bf16 v[20:23], v[194:197], v[178:181], v[20:23]
	v_mfma_f32_16x16x32_bf16 v[16:19], v[210:213], v[178:181], v[16:19]
	v_mfma_f32_16x16x32_bf16 v[4:7], v[194:197], v[186:189], v[4:7]
	v_mfma_f32_16x16x32_bf16 v[0:3], v[210:213], v[186:189], v[0:3]
	v_mfma_f32_16x16x32_bf16 v[52:55], v[198:201], v[166:169], v[52:55]
	v_mfma_f32_16x16x32_bf16 v[48:51], v[214:217], v[166:169], v[48:51]
	v_mfma_f32_16x16x32_bf16 v[36:39], v[198:201], v[174:177], v[36:39]
	v_mfma_f32_16x16x32_bf16 v[32:35], v[214:217], v[174:177], v[32:35]
	v_mfma_f32_16x16x32_bf16 v[20:23], v[198:201], v[182:185], v[20:23]
	v_mfma_f32_16x16x32_bf16 v[16:19], v[214:217], v[182:185], v[16:19]
	v_mfma_f32_16x16x32_bf16 v[4:7], v[198:201], v[190:193], v[4:7]
	v_mfma_f32_16x16x32_bf16 v[0:3], v[214:217], v[190:193], v[0:3]
	s_setprio 0
	s_add_i32 s26, 0, 0x18000
	v_add_u32_e32 v158, s26, v144
	s_barrier
	ds_read_b128 v[146:149], v158
	ds_read_b128 v[150:153], v158 offset:1024
	ds_read_b128 v[154:157], v158 offset:2048
	ds_read_b128 v[158:161], v158 offset:3072
	s_add_u32 s60, s60, 0x40000
	s_addc_u32 s61, s61, 0
	s_mov_b32 m0, s24
	v_lshl_add_u64 v[194:195], s[60:61], 0, v[128:129]
	ds_read_b128 v[162:165], v145 offset:32768
	ds_read_b128 v[166:169], v145 offset:33792
	ds_read_b128 v[170:173], v145 offset:34816
	ds_read_b128 v[174:177], v145 offset:35840
	ds_read_b128 v[178:181], v145 offset:36864
	ds_read_b128 v[182:185], v145 offset:37888
	ds_read_b128 v[186:189], v145 offset:38912
	ds_read_b128 v[190:193], v145 offset:39936
	global_load_lds_dwordx4 v[194:195], off
	v_lshl_add_u64 v[194:195], s[60:61], 0, v[130:131]
	s_mov_b32 m0, s25
	s_nop 0
	global_load_lds_dwordx4 v[194:195], off
	s_waitcnt lgkmcnt(8)
	s_waitcnt vmcnt(10)
	s_barrier
	s_waitcnt lgkmcnt(0)
	s_setprio 1
	s_waitcnt lgkmcnt(0)
	v_mfma_f32_16x16x32_bf16 v[124:127], v[146:149], v[162:165], v[124:127]
	v_mfma_f32_16x16x32_bf16 v[120:123], v[154:157], v[162:165], v[120:123]
	v_mfma_f32_16x16x32_bf16 v[108:111], v[146:149], v[170:173], v[108:111]
	v_mfma_f32_16x16x32_bf16 v[104:107], v[154:157], v[170:173], v[104:107]
	v_mfma_f32_16x16x32_bf16 v[92:95], v[146:149], v[178:181], v[92:95]
	v_mfma_f32_16x16x32_bf16 v[88:91], v[154:157], v[178:181], v[88:91]
	v_mfma_f32_16x16x32_bf16 v[76:79], v[146:149], v[186:189], v[76:79]
	v_mfma_f32_16x16x32_bf16 v[72:75], v[154:157], v[186:189], v[72:75]
	v_mfma_f32_16x16x32_bf16 v[124:127], v[150:153], v[166:169], v[124:127]
	v_mfma_f32_16x16x32_bf16 v[120:123], v[158:161], v[166:169], v[120:123]
	v_mfma_f32_16x16x32_bf16 v[108:111], v[150:153], v[174:177], v[108:111]
	v_mfma_f32_16x16x32_bf16 v[104:107], v[158:161], v[174:177], v[104:107]
	v_mfma_f32_16x16x32_bf16 v[92:95], v[150:153], v[182:185], v[92:95]
	v_mfma_f32_16x16x32_bf16 v[88:91], v[158:161], v[182:185], v[88:91]
	v_mfma_f32_16x16x32_bf16 v[76:79], v[150:153], v[190:193], v[76:79]
	v_mfma_f32_16x16x32_bf16 v[72:75], v[158:161], v[190:193], v[72:75]
	s_setprio 0
	s_barrier
	s_add_i32 s27, 0, 0x1c000
	s_add_i32 s26, s26, s22
	v_add_u32_e32 v209, s27, v144
	v_lshl_add_u64 v[218:219], v[218:219], 0, s[8:9]
	s_mov_b32 m0, s26
	ds_read_b128 v[194:197], v209
	ds_read_b128 v[198:201], v209 offset:1024
	ds_read_b128 v[210:213], v209 offset:2048
	ds_read_b128 v[214:217], v209 offset:3072
	global_load_lds_dwordx4 v[218:219], off
	v_lshl_add_u64 v[218:219], v[220:221], 0, s[8:9]
	s_add_i32 m0, s26, 0x2000
	s_nop 0
	global_load_lds_dwordx4 v[218:219], off
	s_waitcnt vmcnt(10)
	s_barrier
	s_waitcnt lgkmcnt(0)
	s_setprio 1
	s_waitcnt lgkmcnt(0)
	v_mfma_f32_16x16x32_bf16 v[116:119], v[194:197], v[162:165], v[116:119]
	v_mfma_f32_16x16x32_bf16 v[112:115], v[210:213], v[162:165], v[112:115]
	v_mfma_f32_16x16x32_bf16 v[100:103], v[194:197], v[170:173], v[100:103]
	v_mfma_f32_16x16x32_bf16 v[96:99], v[210:213], v[170:173], v[96:99]
	v_mfma_f32_16x16x32_bf16 v[84:87], v[194:197], v[178:181], v[84:87]
	v_mfma_f32_16x16x32_bf16 v[80:83], v[210:213], v[178:181], v[80:83]
	v_mfma_f32_16x16x32_bf16 v[68:71], v[194:197], v[186:189], v[68:71]
	v_mfma_f32_16x16x32_bf16 v[64:67], v[210:213], v[186:189], v[64:67]
	v_mfma_f32_16x16x32_bf16 v[116:119], v[198:201], v[166:169], v[116:119]
	v_mfma_f32_16x16x32_bf16 v[112:115], v[214:217], v[166:169], v[112:115]
	v_mfma_f32_16x16x32_bf16 v[100:103], v[198:201], v[174:177], v[100:103]
	v_mfma_f32_16x16x32_bf16 v[96:99], v[214:217], v[174:177], v[96:99]
	v_mfma_f32_16x16x32_bf16 v[84:87], v[198:201], v[182:185], v[84:87]
	v_mfma_f32_16x16x32_bf16 v[80:83], v[214:217], v[182:185], v[80:83]
	v_mfma_f32_16x16x32_bf16 v[68:71], v[198:201], v[190:193], v[68:71]
	v_mfma_f32_16x16x32_bf16 v[64:67], v[214:217], v[190:193], v[64:67]
	s_setprio 0
	s_mov_b32 m0, s33
	v_lshl_add_u64 v[218:219], v[222:223], 0, s[8:9]
	s_barrier
	ds_read_b128 v[162:165], v145 offset:49152
	ds_read_b128 v[166:169], v145 offset:50176
	ds_read_b128 v[170:173], v145 offset:51200
	ds_read_b128 v[174:177], v145 offset:52224
	ds_read_b128 v[178:181], v145 offset:53248
	ds_read_b128 v[182:185], v145 offset:54272
	ds_read_b128 v[186:189], v145 offset:55296
	ds_read_b128 v[190:193], v145 offset:56320
	global_load_lds_dwordx4 v[218:219], off
	v_lshl_add_u64 v[218:219], v[224:225], 0, s[8:9]
	s_mov_b32 m0, s62
	s_nop 0
	global_load_lds_dwordx4 v[218:219], off
	s_barrier
	s_waitcnt lgkmcnt(0)
	s_setprio 1
	s_waitcnt lgkmcnt(0)
	v_mfma_f32_16x16x32_bf16 v[60:63], v[146:149], v[162:165], v[60:63]
	v_mfma_f32_16x16x32_bf16 v[56:59], v[154:157], v[162:165], v[56:59]
	v_mfma_f32_16x16x32_bf16 v[44:47], v[146:149], v[170:173], v[44:47]
	v_mfma_f32_16x16x32_bf16 v[40:43], v[154:157], v[170:173], v[40:43]
	v_mfma_f32_16x16x32_bf16 v[28:31], v[146:149], v[178:181], v[28:31]
	v_mfma_f32_16x16x32_bf16 v[24:27], v[154:157], v[178:181], v[24:27]
	v_mfma_f32_16x16x32_bf16 v[12:15], v[146:149], v[186:189], v[12:15]
	v_mfma_f32_16x16x32_bf16 v[8:11], v[154:157], v[186:189], v[8:11]
	v_mfma_f32_16x16x32_bf16 v[60:63], v[150:153], v[166:169], v[60:63]
	v_mfma_f32_16x16x32_bf16 v[56:59], v[158:161], v[166:169], v[56:59]
	v_mfma_f32_16x16x32_bf16 v[44:47], v[150:153], v[174:177], v[44:47]
	v_mfma_f32_16x16x32_bf16 v[40:43], v[158:161], v[174:177], v[40:43]
	v_mfma_f32_16x16x32_bf16 v[28:31], v[150:153], v[182:185], v[28:31]
	v_mfma_f32_16x16x32_bf16 v[24:27], v[158:161], v[182:185], v[24:27]
	v_mfma_f32_16x16x32_bf16 v[12:15], v[150:153], v[190:193], v[12:15]
	v_mfma_f32_16x16x32_bf16 v[8:11], v[158:161], v[190:193], v[8:11]
	s_setprio 0
	s_barrier
	s_add_u32 s58, s58, 0x40080
	s_addc_u32 s59, s59, 0
	s_add_i32 s26, s27, s22
	v_lshl_add_u64 v[146:147], s[58:59], 0, v[128:129]
	s_mov_b32 m0, s26
	s_nop 0
	global_load_lds_dwordx4 v[146:147], off
	v_lshl_add_u64 v[146:147], s[58:59], 0, v[130:131]
	s_add_i32 m0, s26, 0x2000
	s_nop 0
	global_load_lds_dwordx4 v[146:147], off
	s_waitcnt vmcnt(10)
	s_barrier
	s_setprio 1
	v_mfma_f32_16x16x32_bf16 v[52:55], v[194:197], v[162:165], v[52:55]
	v_mfma_f32_16x16x32_bf16 v[48:51], v[210:213], v[162:165], v[48:51]
	v_mfma_f32_16x16x32_bf16 v[36:39], v[194:197], v[170:173], v[36:39]
	v_mfma_f32_16x16x32_bf16 v[32:35], v[210:213], v[170:173], v[32:35]
	v_mfma_f32_16x16x32_bf16 v[20:23], v[194:197], v[178:181], v[20:23]
	v_mfma_f32_16x16x32_bf16 v[16:19], v[210:213], v[178:181], v[16:19]
	v_mfma_f32_16x16x32_bf16 v[4:7], v[194:197], v[186:189], v[4:7]
	v_mfma_f32_16x16x32_bf16 v[0:3], v[210:213], v[186:189], v[0:3]
	v_mfma_f32_16x16x32_bf16 v[52:55], v[198:201], v[166:169], v[52:55]
	v_mfma_f32_16x16x32_bf16 v[48:51], v[214:217], v[166:169], v[48:51]
	v_mfma_f32_16x16x32_bf16 v[36:39], v[198:201], v[174:177], v[36:39]
	v_mfma_f32_16x16x32_bf16 v[32:35], v[214:217], v[174:177], v[32:35]
	v_mfma_f32_16x16x32_bf16 v[20:23], v[198:201], v[182:185], v[20:23]
	v_mfma_f32_16x16x32_bf16 v[16:19], v[214:217], v[182:185], v[16:19]
	v_mfma_f32_16x16x32_bf16 v[4:7], v[198:201], v[190:193], v[4:7]
	v_mfma_f32_16x16x32_bf16 v[0:3], v[214:217], v[190:193], v[0:3]
	s_setprio 0
	s_add_i32 s71, s71, 2
	s_add_u32 s56, s56, 0x100
	s_addc_u32 s57, s57, 0
	s_cmp_gt_u32 s71, 13
	s_barrier
	s_cbranch_scc0 .LBB0_898
	s_add_u32 s56, s67, 0xffffff00
	s_addc_u32 s57, s68, -1
	s_andn2_b64 vcc, exec, s[4:5]
	s_cbranch_vccnz .LBB0_889
	v_mov_b32_e32 v0, 0
	s_mov_b32 s13, s14
	s_mov_b32 s2, s16
	s_mov_b64 s[6:7], s[38:39]
	s_mov_b32 s63, s66
	v_mov_b32_e32 v1, v0
	v_mov_b32_e32 v2, v0
	v_mov_b32_e32 v3, v0
	v_mov_b32_e32 v4, v0
	v_mov_b32_e32 v5, v0
	v_mov_b32_e32 v6, v0
	v_mov_b32_e32 v7, v0
	v_mov_b32_e32 v16, v0
	v_mov_b32_e32 v17, v0
	v_mov_b32_e32 v18, v0
	v_mov_b32_e32 v19, v0
	v_mov_b32_e32 v20, v0
	v_mov_b32_e32 v21, v0
	v_mov_b32_e32 v22, v0
	v_mov_b32_e32 v23, v0
	v_mov_b32_e32 v32, v0
	v_mov_b32_e32 v33, v0
	v_mov_b32_e32 v34, v0
	v_mov_b32_e32 v35, v0
	v_mov_b32_e32 v36, v0
	v_mov_b32_e32 v37, v0
	v_mov_b32_e32 v38, v0
	v_mov_b32_e32 v39, v0
	v_mov_b32_e32 v48, v0
	v_mov_b32_e32 v49, v0
	v_mov_b32_e32 v50, v0
	v_mov_b32_e32 v51, v0
	v_mov_b32_e32 v52, v0
	v_mov_b32_e32 v53, v0
	v_mov_b32_e32 v54, v0
	v_mov_b32_e32 v55, v0
	v_mov_b32_e32 v8, v0
	v_mov_b32_e32 v9, v0
	v_mov_b32_e32 v10, v0
	v_mov_b32_e32 v11, v0
	v_mov_b32_e32 v12, v0
	v_mov_b32_e32 v13, v0
	v_mov_b32_e32 v14, v0
	v_mov_b32_e32 v15, v0
	v_mov_b32_e32 v24, v0
	v_mov_b32_e32 v25, v0
	v_mov_b32_e32 v26, v0
	v_mov_b32_e32 v27, v0
	v_mov_b32_e32 v28, v0
	v_mov_b32_e32 v29, v0
	v_mov_b32_e32 v30, v0
	v_mov_b32_e32 v31, v0
	v_mov_b32_e32 v40, v0
	v_mov_b32_e32 v41, v0
	v_mov_b32_e32 v42, v0
	v_mov_b32_e32 v43, v0
	v_mov_b32_e32 v44, v0
	v_mov_b32_e32 v45, v0
	v_mov_b32_e32 v46, v0
	v_mov_b32_e32 v47, v0
	v_mov_b32_e32 v56, v0
	v_mov_b32_e32 v57, v0
	v_mov_b32_e32 v58, v0
	v_mov_b32_e32 v59, v0
	v_mov_b32_e32 v60, v0
	v_mov_b32_e32 v61, v0
	v_mov_b32_e32 v62, v0
	v_mov_b32_e32 v63, v0
	v_mov_b32_e32 v64, v0
	v_mov_b32_e32 v65, v0
	v_mov_b32_e32 v66, v0
	v_mov_b32_e32 v67, v0
	v_mov_b32_e32 v68, v0
	v_mov_b32_e32 v69, v0
	v_mov_b32_e32 v70, v0
	v_mov_b32_e32 v71, v0
	v_mov_b32_e32 v80, v0
	v_mov_b32_e32 v81, v0
	v_mov_b32_e32 v82, v0
	v_mov_b32_e32 v83, v0
	v_mov_b32_e32 v84, v0
	v_mov_b32_e32 v85, v0
	v_mov_b32_e32 v86, v0
	v_mov_b32_e32 v87, v0
	v_mov_b32_e32 v96, v0
	v_mov_b32_e32 v97, v0
	v_mov_b32_e32 v98, v0
	v_mov_b32_e32 v99, v0
	v_mov_b32_e32 v100, v0
	v_mov_b32_e32 v101, v0
	v_mov_b32_e32 v102, v0
	v_mov_b32_e32 v103, v0
	v_mov_b32_e32 v112, v0
	v_mov_b32_e32 v113, v0
	v_mov_b32_e32 v114, v0
	v_mov_b32_e32 v115, v0
	v_mov_b32_e32 v116, v0
	v_mov_b32_e32 v117, v0
	v_mov_b32_e32 v118, v0
	v_mov_b32_e32 v119, v0
	v_mov_b32_e32 v72, v0
	v_mov_b32_e32 v73, v0
	v_mov_b32_e32 v74, v0
	v_mov_b32_e32 v75, v0
	v_mov_b32_e32 v76, v0
	v_mov_b32_e32 v77, v0
	v_mov_b32_e32 v78, v0
	v_mov_b32_e32 v79, v0
	v_mov_b32_e32 v88, v0
	v_mov_b32_e32 v89, v0
	v_mov_b32_e32 v90, v0
	v_mov_b32_e32 v91, v0
	v_mov_b32_e32 v92, v0
	v_mov_b32_e32 v93, v0
	v_mov_b32_e32 v94, v0
	v_mov_b32_e32 v95, v0
	v_mov_b32_e32 v104, v0
	v_mov_b32_e32 v105, v0
	v_mov_b32_e32 v106, v0
	v_mov_b32_e32 v107, v0
	v_mov_b32_e32 v108, v0
	v_mov_b32_e32 v109, v0
	v_mov_b32_e32 v110, v0
	v_mov_b32_e32 v111, v0
	v_mov_b32_e32 v120, v0
	v_mov_b32_e32 v121, v0
	v_mov_b32_e32 v122, v0
	v_mov_b32_e32 v123, v0
	v_mov_b32_e32 v124, v0
	v_mov_b32_e32 v125, v0
	v_mov_b32_e32 v126, v0
	v_mov_b32_e32 v127, v0
	s_andn2_b64 vcc, exec, s[0:1]
	s_cbranch_vccnz .LBB0_890
